# bundle: nt in-proj stores + P0a silu fill loads in flight + P4 rows double-buffered + P3a epilogue gate loads up front
# speedup vs baseline: 1.0215x; 1.0147x over previous
.LBB0_9:
	s_and_saveexec_b64 s[14:15], vcc
	s_cbranch_execz .LBB0_16
	s_load_dwordx2 s[28:29], s[0:1], 0x8
	s_load_dwordx2 s[16:17], s[0:1], 0x18
	v_add_u32_e32 v155, 0x10000, v5
	s_waitcnt lgkmcnt(0)
	global_load_dword v120, v5, s[28:29]
	global_load_dword v121, v5, s[28:29] offset:2048
	s_add_u32 s28, s28, 0x1000
	s_addc_u32 s29, s29, 0
	global_load_dword v122, v5, s[28:29]
	global_load_dword v123, v5, s[28:29] offset:2048
	s_add_u32 s28, s28, 0x1000
	s_addc_u32 s29, s29, 0
	global_load_dword v124, v5, s[28:29]
	global_load_dword v125, v5, s[28:29] offset:2048
	s_add_u32 s28, s28, 0x1000
	s_addc_u32 s29, s29, 0
	global_load_dword v126, v5, s[28:29]
	global_load_dword v127, v5, s[28:29] offset:2048
	s_add_u32 s28, s28, 0x1000
	s_addc_u32 s29, s29, 0
	global_load_dword v128, v5, s[28:29]
	global_load_dword v129, v5, s[28:29] offset:2048
	s_add_u32 s28, s28, 0x1000
	s_addc_u32 s29, s29, 0
	global_load_dword v130, v5, s[28:29]
	global_load_dword v131, v5, s[28:29] offset:2048
	s_add_u32 s28, s28, 0x1000
	s_addc_u32 s29, s29, 0
	global_load_dword v132, v5, s[28:29]
	global_load_dword v133, v5, s[28:29] offset:2048
	s_add_u32 s28, s28, 0x1000
	s_addc_u32 s29, s29, 0
	global_load_dword v134, v5, s[28:29]
	global_load_dword v135, v5, s[28:29] offset:2048
	s_add_u32 s28, s28, 0x1000
	s_addc_u32 s29, s29, 0
	global_load_dword v136, v5, s[28:29]
	global_load_dword v137, v5, s[28:29] offset:2048
	s_add_u32 s28, s28, 0x1000
	s_addc_u32 s29, s29, 0
	global_load_dword v138, v5, s[28:29]
	global_load_dword v139, v5, s[28:29] offset:2048
	s_add_u32 s28, s28, 0x1000
	s_addc_u32 s29, s29, 0
	global_load_dword v140, v5, s[28:29]
	global_load_dword v141, v5, s[28:29] offset:2048
	s_add_u32 s28, s28, 0x1000
	s_addc_u32 s29, s29, 0
	global_load_dword v142, v5, s[28:29]
	global_load_dword v143, v5, s[28:29] offset:2048
	s_add_u32 s28, s28, 0x1000
	s_addc_u32 s29, s29, 0
	global_load_dword v144, v5, s[28:29]
	global_load_dword v145, v5, s[28:29] offset:2048
	s_add_u32 s28, s28, 0x1000
	s_addc_u32 s29, s29, 0
	global_load_dword v146, v5, s[28:29]
	global_load_dword v147, v5, s[28:29] offset:2048
	s_add_u32 s28, s28, 0x1000
	s_addc_u32 s29, s29, 0
	global_load_dword v148, v5, s[28:29]
	global_load_dword v149, v5, s[28:29] offset:2048
	s_add_u32 s28, s28, 0x1000
	s_addc_u32 s29, s29, 0
	global_load_dword v150, v5, s[28:29]
	global_load_dword v151, v5, s[28:29] offset:2048
	global_load_dword v152, v5, s[16:17]
	global_load_dword v153, v5, s[16:17] offset:2048
	s_waitcnt vmcnt(32)
	v_mul_f32_e32 v156, 0xbfb8aa3b, v120
	v_mul_f32_e32 v157, 0xbfb8aa3b, v121
	v_exp_f32_e32 v156, v156
	v_exp_f32_e32 v157, v157
	v_add_f32_e32 v156, 1.0, v156
	v_add_f32_e32 v157, 1.0, v157
	v_rcp_f32_e32 v156, v156
	v_rcp_f32_e32 v157, v157
	v_mul_f32_e32 v120, v120, v156
	v_mul_f32_e32 v121, v121, v157
	ds_write_b32 v5, v120
	ds_write_b32 v5, v121 offset:2048
	s_waitcnt vmcnt(30)
	v_mul_f32_e32 v156, 0xbfb8aa3b, v122
	v_mul_f32_e32 v157, 0xbfb8aa3b, v123
	v_exp_f32_e32 v156, v156
	v_exp_f32_e32 v157, v157
	v_add_f32_e32 v156, 1.0, v156
	v_add_f32_e32 v157, 1.0, v157
	v_rcp_f32_e32 v156, v156
	v_rcp_f32_e32 v157, v157
	v_mul_f32_e32 v122, v122, v156
	v_mul_f32_e32 v123, v123, v157
	ds_write_b32 v5, v122 offset:4096
	ds_write_b32 v5, v123 offset:6144
	s_waitcnt vmcnt(28)
	v_mul_f32_e32 v156, 0xbfb8aa3b, v124
	v_mul_f32_e32 v157, 0xbfb8aa3b, v125
	v_exp_f32_e32 v156, v156
	v_exp_f32_e32 v157, v157
	v_add_f32_e32 v156, 1.0, v156
	v_add_f32_e32 v157, 1.0, v157
	v_rcp_f32_e32 v156, v156
	v_rcp_f32_e32 v157, v157
	v_mul_f32_e32 v124, v124, v156
	v_mul_f32_e32 v125, v125, v157
	ds_write_b32 v5, v124 offset:8192
	ds_write_b32 v5, v125 offset:10240
	s_waitcnt vmcnt(26)
	v_mul_f32_e32 v156, 0xbfb8aa3b, v126
	v_mul_f32_e32 v157, 0xbfb8aa3b, v127
	v_exp_f32_e32 v156, v156
	v_exp_f32_e32 v157, v157
	v_add_f32_e32 v156, 1.0, v156
	v_add_f32_e32 v157, 1.0, v157
	v_rcp_f32_e32 v156, v156
	v_rcp_f32_e32 v157, v157
	v_mul_f32_e32 v126, v126, v156
	v_mul_f32_e32 v127, v127, v157
	ds_write_b32 v5, v126 offset:12288
	ds_write_b32 v5, v127 offset:14336
	s_waitcnt vmcnt(24)
	v_mul_f32_e32 v156, 0xbfb8aa3b, v128
	v_mul_f32_e32 v157, 0xbfb8aa3b, v129
	v_exp_f32_e32 v156, v156
	v_exp_f32_e32 v157, v157
	v_add_f32_e32 v156, 1.0, v156
	v_add_f32_e32 v157, 1.0, v157
	v_rcp_f32_e32 v156, v156
	v_rcp_f32_e32 v157, v157
	v_mul_f32_e32 v128, v128, v156
	v_mul_f32_e32 v129, v129, v157
	ds_write_b32 v5, v128 offset:16384
	ds_write_b32 v5, v129 offset:18432
	s_waitcnt vmcnt(22)
	v_mul_f32_e32 v156, 0xbfb8aa3b, v130
	v_mul_f32_e32 v157, 0xbfb8aa3b, v131
	v_exp_f32_e32 v156, v156
	v_exp_f32_e32 v157, v157
	v_add_f32_e32 v156, 1.0, v156
	v_add_f32_e32 v157, 1.0, v157
	v_rcp_f32_e32 v156, v156
	v_rcp_f32_e32 v157, v157
	v_mul_f32_e32 v130, v130, v156
	v_mul_f32_e32 v131, v131, v157
	ds_write_b32 v5, v130 offset:20480
	ds_write_b32 v5, v131 offset:22528
	s_waitcnt vmcnt(20)
	v_mul_f32_e32 v156, 0xbfb8aa3b, v132
	v_mul_f32_e32 v157, 0xbfb8aa3b, v133
	v_exp_f32_e32 v156, v156
	v_exp_f32_e32 v157, v157
	v_add_f32_e32 v156, 1.0, v156
	v_add_f32_e32 v157, 1.0, v157
	v_rcp_f32_e32 v156, v156
	v_rcp_f32_e32 v157, v157
	v_mul_f32_e32 v132, v132, v156
	v_mul_f32_e32 v133, v133, v157
	ds_write_b32 v5, v132 offset:24576
	ds_write_b32 v5, v133 offset:26624
	s_waitcnt vmcnt(18)
	v_mul_f32_e32 v156, 0xbfb8aa3b, v134
	v_mul_f32_e32 v157, 0xbfb8aa3b, v135
	v_exp_f32_e32 v156, v156
	v_exp_f32_e32 v157, v157
	v_add_f32_e32 v156, 1.0, v156
	v_add_f32_e32 v157, 1.0, v157
	v_rcp_f32_e32 v156, v156
	v_rcp_f32_e32 v157, v157
	v_mul_f32_e32 v134, v134, v156
	v_mul_f32_e32 v135, v135, v157
	ds_write_b32 v5, v134 offset:28672
	ds_write_b32 v5, v135 offset:30720
	s_waitcnt vmcnt(16)
	v_mul_f32_e32 v156, 0xbfb8aa3b, v136
	v_mul_f32_e32 v157, 0xbfb8aa3b, v137
	v_exp_f32_e32 v156, v156
	v_exp_f32_e32 v157, v157
	v_add_f32_e32 v156, 1.0, v156
	v_add_f32_e32 v157, 1.0, v157
	v_rcp_f32_e32 v156, v156
	v_rcp_f32_e32 v157, v157
	v_mul_f32_e32 v136, v136, v156
	v_mul_f32_e32 v137, v137, v157
	ds_write_b32 v5, v136 offset:32768
	ds_write_b32 v5, v137 offset:34816
	s_waitcnt vmcnt(14)
	v_mul_f32_e32 v156, 0xbfb8aa3b, v138
	v_mul_f32_e32 v157, 0xbfb8aa3b, v139
	v_exp_f32_e32 v156, v156
	v_exp_f32_e32 v157, v157
	v_add_f32_e32 v156, 1.0, v156
	v_add_f32_e32 v157, 1.0, v157
	v_rcp_f32_e32 v156, v156
	v_rcp_f32_e32 v157, v157
	v_mul_f32_e32 v138, v138, v156
	v_mul_f32_e32 v139, v139, v157
	ds_write_b32 v5, v138 offset:36864
	ds_write_b32 v5, v139 offset:38912
	s_waitcnt vmcnt(12)
	v_mul_f32_e32 v156, 0xbfb8aa3b, v140
	v_mul_f32_e32 v157, 0xbfb8aa3b, v141
	v_exp_f32_e32 v156, v156
	v_exp_f32_e32 v157, v157
	v_add_f32_e32 v156, 1.0, v156
	v_add_f32_e32 v157, 1.0, v157
	v_rcp_f32_e32 v156, v156
	v_rcp_f32_e32 v157, v157
	v_mul_f32_e32 v140, v140, v156
	v_mul_f32_e32 v141, v141, v157
	ds_write_b32 v5, v140 offset:40960
	ds_write_b32 v5, v141 offset:43008
	s_waitcnt vmcnt(10)
	v_mul_f32_e32 v156, 0xbfb8aa3b, v142
	v_mul_f32_e32 v157, 0xbfb8aa3b, v143
	v_exp_f32_e32 v156, v156
	v_exp_f32_e32 v157, v157
	v_add_f32_e32 v156, 1.0, v156
	v_add_f32_e32 v157, 1.0, v157
	v_rcp_f32_e32 v156, v156
	v_rcp_f32_e32 v157, v157
	v_mul_f32_e32 v142, v142, v156
	v_mul_f32_e32 v143, v143, v157
	ds_write_b32 v5, v142 offset:45056
	ds_write_b32 v5, v143 offset:47104
	s_waitcnt vmcnt(8)
	v_mul_f32_e32 v156, 0xbfb8aa3b, v144
	v_mul_f32_e32 v157, 0xbfb8aa3b, v145
	v_exp_f32_e32 v156, v156
	v_exp_f32_e32 v157, v157
	v_add_f32_e32 v156, 1.0, v156
	v_add_f32_e32 v157, 1.0, v157
	v_rcp_f32_e32 v156, v156
	v_rcp_f32_e32 v157, v157
	v_mul_f32_e32 v144, v144, v156
	v_mul_f32_e32 v145, v145, v157
	ds_write_b32 v5, v144 offset:49152
	ds_write_b32 v5, v145 offset:51200
	s_waitcnt vmcnt(6)
	v_mul_f32_e32 v156, 0xbfb8aa3b, v146
	v_mul_f32_e32 v157, 0xbfb8aa3b, v147
	v_exp_f32_e32 v156, v156
	v_exp_f32_e32 v157, v157
	v_add_f32_e32 v156, 1.0, v156
	v_add_f32_e32 v157, 1.0, v157
	v_rcp_f32_e32 v156, v156
	v_rcp_f32_e32 v157, v157
	v_mul_f32_e32 v146, v146, v156
	v_mul_f32_e32 v147, v147, v157
	ds_write_b32 v5, v146 offset:53248
	ds_write_b32 v5, v147 offset:55296
	s_waitcnt vmcnt(4)
	v_mul_f32_e32 v156, 0xbfb8aa3b, v148
	v_mul_f32_e32 v157, 0xbfb8aa3b, v149
	v_exp_f32_e32 v156, v156
	v_exp_f32_e32 v157, v157
	v_add_f32_e32 v156, 1.0, v156
	v_add_f32_e32 v157, 1.0, v157
	v_rcp_f32_e32 v156, v156
	v_rcp_f32_e32 v157, v157
	v_mul_f32_e32 v148, v148, v156
	v_mul_f32_e32 v149, v149, v157
	ds_write_b32 v5, v148 offset:57344
	ds_write_b32 v5, v149 offset:59392
	s_waitcnt vmcnt(2)
	v_mul_f32_e32 v156, 0xbfb8aa3b, v150
	v_mul_f32_e32 v157, 0xbfb8aa3b, v151
	v_exp_f32_e32 v156, v156
	v_exp_f32_e32 v157, v157
	v_add_f32_e32 v156, 1.0, v156
	v_add_f32_e32 v157, 1.0, v157
	v_rcp_f32_e32 v156, v156
	v_rcp_f32_e32 v157, v157
	v_mul_f32_e32 v150, v150, v156
	v_mul_f32_e32 v151, v151, v157
	ds_write_b32 v5, v150 offset:61440
	ds_write_b32 v5, v151 offset:63488
	s_waitcnt vmcnt(0)
	v_mul_f32_e32 v156, 0xbfb8aa3b, v152
	v_mul_f32_e32 v157, 0xbfb8aa3b, v153
	v_exp_f32_e32 v156, v156
	v_exp_f32_e32 v157, v157
	v_add_f32_e32 v156, 1.0, v156
	v_add_f32_e32 v157, 1.0, v157
	v_rcp_f32_e32 v156, v156
	v_rcp_f32_e32 v157, v157
	v_mul_f32_e32 v152, v152, v156
	v_mul_f32_e32 v153, v153, v157
	ds_write_b32 v155, v152
	ds_write_b32 v155, v153 offset:2048

.LBB0_510:
	s_cmpk_gt_i32 s8, 0x7f
	s_cselect_b64 s[62:63], -1, 0
	s_lshl_b32 s37, s60, 8
	s_add_i32 s9, s8, 0xffffff80
	s_add_i32 s39, s37, 0xfffffc00
	s_cmpk_lt_i32 s8, 0x80
	s_cselect_b32 s8, s8, s9
	s_cselect_b32 s37, s37, s39
	s_ashr_i32 s9, s8, 31
	s_lshl_b64 s[8:9], s[8:9], 19
	v_or_b32_e32 v146, s37, v165
	v_lshl_add_u64 v[228:229], s[8:9], 0, v[136:137]
	v_lshl_add_u64 v[196:197], v[228:229], 1, s[52:53]
	v_ashrrev_i32_e32 v147, 31, v146
	v_lshl_add_u64 v[196:197], v[146:147], 1, v[196:197]
	v_lshl_add_u64 v[206:207], s[54:55], 0, v[228:229]
	v_lshl_add_u64 v[206:207], v[146:147], 1, v[206:207]
	s_mov_b64 s[60:61], 0x10000
	s_and_b64 vcc, exec, s[62:63]
	s_cbranch_vccz .Lp3a_epi_first
	s_mov_b64 s[8:9], 0x8000
	global_load_dwordx4 v[168:171], v[196:197], off offset:2048
	global_load_dwordx4 v[172:175], v[196:197], off offset:2304
	v_lshl_add_u64 v[146:147], v[196:197], 0, s[60:61]
	global_load_dwordx4 v[176:179], v[146:147], off offset:2048
	global_load_dwordx4 v[180:183], v[146:147], off offset:2304
	v_lshl_add_u64 v[146:147], v[146:147], 0, s[60:61]
	global_load_dwordx4 v[184:187], v[146:147], off offset:2048
	global_load_dwordx4 v[188:191], v[146:147], off offset:2304
	v_lshl_add_u64 v[146:147], v[146:147], 0, s[60:61]
	global_load_dwordx4 v[192:195], v[146:147], off offset:2048
	global_load_dwordx4 v[208:211], v[146:147], off offset:2304
	v_lshl_add_u64 v[146:147], v[196:197], 0, s[18:19]
	global_load_dwordx4 v[212:215], v[146:147], off offset:2048
	global_load_dwordx4 v[216:219], v[146:147], off offset:2304
	v_lshl_add_u64 v[146:147], v[196:197], 0, s[22:23]
	global_load_dwordx4 v[220:223], v[146:147], off offset:2048
	global_load_dwordx4 v[224:227], v[146:147], off offset:2304
	v_lshl_add_u64 v[146:147], v[196:197], 0, s[26:27]
	global_load_dwordx4 v[232:235], v[146:147], off offset:2048
	global_load_dwordx4 v[236:239], v[146:147], off offset:2304
	v_lshl_add_u64 v[146:147], v[196:197], 0, s[30:31]
	global_load_dwordx4 v[240:243], v[146:147], off offset:2048
	global_load_dwordx4 v[244:247], v[146:147], off offset:2304
	s_waitcnt vmcnt(15)
	v_lshlrev_b32_e32 v148, 16, v168
	v_and_b32_e32 v149, 0xffff0000, v168
	v_lshlrev_b32_e32 v150, 16, v169
	v_and_b32_e32 v151, 0xffff0000, v169
	v_pk_mul_f32 v[148:149], v[124:125], v[148:149]
	v_pk_mul_f32 v[150:151], v[126:127], v[150:151]
	v_cvt_pk_bf16_f32 v168, v148, v149
	v_cvt_pk_bf16_f32 v169, v150, v151
	v_lshlrev_b32_e32 v148, 16, v170
	v_and_b32_e32 v149, 0xffff0000, v170
	v_lshlrev_b32_e32 v150, 16, v171
	v_and_b32_e32 v151, 0xffff0000, v171
	v_pk_mul_f32 v[148:149], v[120:121], v[148:149]
	v_pk_mul_f32 v[150:151], v[122:123], v[150:151]
	v_cvt_pk_bf16_f32 v170, v148, v149
	v_cvt_pk_bf16_f32 v171, v150, v151
	global_store_dwordx4 v[206:207], v[168:171], off
	s_waitcnt vmcnt(15)
	v_lshlrev_b32_e32 v148, 16, v172
	v_and_b32_e32 v149, 0xffff0000, v172
	v_lshlrev_b32_e32 v150, 16, v173
	v_and_b32_e32 v151, 0xffff0000, v173
	v_pk_mul_f32 v[148:149], v[92:93], v[148:149]
	v_pk_mul_f32 v[150:151], v[94:95], v[150:151]
	v_cvt_pk_bf16_f32 v172, v148, v149
	v_cvt_pk_bf16_f32 v173, v150, v151
	v_lshlrev_b32_e32 v148, 16, v174
	v_and_b32_e32 v149, 0xffff0000, v174
	v_lshlrev_b32_e32 v150, 16, v175
	v_and_b32_e32 v151, 0xffff0000, v175
	v_pk_mul_f32 v[148:149], v[88:89], v[148:149]
	v_pk_mul_f32 v[150:151], v[90:91], v[150:151]
	v_cvt_pk_bf16_f32 v174, v148, v149
	v_cvt_pk_bf16_f32 v175, v150, v151
	global_store_dwordx4 v[206:207], v[172:175], off offset:256
	s_waitcnt vmcnt(15)
	v_lshlrev_b32_e32 v148, 16, v176
	v_and_b32_e32 v149, 0xffff0000, v176
	v_lshlrev_b32_e32 v150, 16, v177
	v_and_b32_e32 v151, 0xffff0000, v177
	v_pk_mul_f32 v[148:149], v[116:117], v[148:149]
	v_pk_mul_f32 v[150:151], v[118:119], v[150:151]
	v_cvt_pk_bf16_f32 v176, v148, v149
	v_cvt_pk_bf16_f32 v177, v150, v151
	v_lshlrev_b32_e32 v148, 16, v178
	v_and_b32_e32 v149, 0xffff0000, v178
	v_lshlrev_b32_e32 v150, 16, v179
	v_and_b32_e32 v151, 0xffff0000, v179
	v_pk_mul_f32 v[148:149], v[112:113], v[148:149]
	v_pk_mul_f32 v[150:151], v[114:115], v[150:151]
	v_cvt_pk_bf16_f32 v178, v148, v149
	v_cvt_pk_bf16_f32 v179, v150, v151
	v_lshl_add_u64 v[146:147], v[206:207], 0, s[8:9]
	global_store_dwordx4 v[146:147], v[176:179], off
	s_waitcnt vmcnt(15)
	v_lshlrev_b32_e32 v148, 16, v180
	v_and_b32_e32 v149, 0xffff0000, v180
	v_lshlrev_b32_e32 v150, 16, v181
	v_and_b32_e32 v151, 0xffff0000, v181
	v_pk_mul_f32 v[148:149], v[84:85], v[148:149]
	v_pk_mul_f32 v[150:151], v[86:87], v[150:151]
	v_cvt_pk_bf16_f32 v180, v148, v149
	v_cvt_pk_bf16_f32 v181, v150, v151
	v_lshlrev_b32_e32 v148, 16, v182
	v_and_b32_e32 v149, 0xffff0000, v182
	v_lshlrev_b32_e32 v150, 16, v183
	v_and_b32_e32 v151, 0xffff0000, v183
	v_pk_mul_f32 v[148:149], v[80:81], v[148:149]
	v_pk_mul_f32 v[150:151], v[82:83], v[150:151]
	v_cvt_pk_bf16_f32 v182, v148, v149
	v_cvt_pk_bf16_f32 v183, v150, v151
	global_store_dwordx4 v[146:147], v[180:183], off offset:256
	s_waitcnt vmcnt(15)
	v_lshlrev_b32_e32 v148, 16, v184
	v_and_b32_e32 v149, 0xffff0000, v184
	v_lshlrev_b32_e32 v150, 16, v185
	v_and_b32_e32 v151, 0xffff0000, v185
	v_pk_mul_f32 v[148:149], v[108:109], v[148:149]
	v_pk_mul_f32 v[150:151], v[110:111], v[150:151]
	v_cvt_pk_bf16_f32 v184, v148, v149
	v_cvt_pk_bf16_f32 v185, v150, v151
	v_lshlrev_b32_e32 v148, 16, v186
	v_and_b32_e32 v149, 0xffff0000, v186
	v_lshlrev_b32_e32 v150, 16, v187
	v_and_b32_e32 v151, 0xffff0000, v187
	v_pk_mul_f32 v[148:149], v[104:105], v[148:149]
	v_pk_mul_f32 v[150:151], v[106:107], v[150:151]
	v_cvt_pk_bf16_f32 v186, v148, v149
	v_cvt_pk_bf16_f32 v187, v150, v151
	v_lshl_add_u64 v[146:147], v[146:147], 0, s[8:9]
	global_store_dwordx4 v[146:147], v[184:187], off
	s_waitcnt vmcnt(15)
	v_lshlrev_b32_e32 v148, 16, v188
	v_and_b32_e32 v149, 0xffff0000, v188
	v_lshlrev_b32_e32 v150, 16, v189
	v_and_b32_e32 v151, 0xffff0000, v189
	v_pk_mul_f32 v[148:149], v[76:77], v[148:149]
	v_pk_mul_f32 v[150:151], v[78:79], v[150:151]
	v_cvt_pk_bf16_f32 v188, v148, v149
	v_cvt_pk_bf16_f32 v189, v150, v151
	v_lshlrev_b32_e32 v148, 16, v190
	v_and_b32_e32 v149, 0xffff0000, v190
	v_lshlrev_b32_e32 v150, 16, v191
	v_and_b32_e32 v151, 0xffff0000, v191
	v_pk_mul_f32 v[148:149], v[72:73], v[148:149]
	v_pk_mul_f32 v[150:151], v[74:75], v[150:151]
	v_cvt_pk_bf16_f32 v190, v148, v149
	v_cvt_pk_bf16_f32 v191, v150, v151
	global_store_dwordx4 v[146:147], v[188:191], off offset:256
	s_waitcnt vmcnt(15)
	v_lshlrev_b32_e32 v148, 16, v192
	v_and_b32_e32 v149, 0xffff0000, v192
	v_lshlrev_b32_e32 v150, 16, v193
	v_and_b32_e32 v151, 0xffff0000, v193
	v_pk_mul_f32 v[148:149], v[100:101], v[148:149]
	v_pk_mul_f32 v[150:151], v[102:103], v[150:151]
	v_cvt_pk_bf16_f32 v192, v148, v149
	v_cvt_pk_bf16_f32 v193, v150, v151
	v_lshlrev_b32_e32 v148, 16, v194
	v_and_b32_e32 v149, 0xffff0000, v194
	v_lshlrev_b32_e32 v150, 16, v195
	v_and_b32_e32 v151, 0xffff0000, v195
	v_pk_mul_f32 v[148:149], v[96:97], v[148:149]
	v_pk_mul_f32 v[150:151], v[98:99], v[150:151]
	v_cvt_pk_bf16_f32 v194, v148, v149
	v_cvt_pk_bf16_f32 v195, v150, v151
	v_lshl_add_u64 v[146:147], v[146:147], 0, s[8:9]
	global_store_dwordx4 v[146:147], v[192:195], off
	s_waitcnt vmcnt(15)
	v_lshlrev_b32_e32 v148, 16, v208
	v_and_b32_e32 v149, 0xffff0000, v208
	v_lshlrev_b32_e32 v150, 16, v209
	v_and_b32_e32 v151, 0xffff0000, v209
	v_pk_mul_f32 v[148:149], v[68:69], v[148:149]
	v_pk_mul_f32 v[150:151], v[70:71], v[150:151]
	v_cvt_pk_bf16_f32 v208, v148, v149
	v_cvt_pk_bf16_f32 v209, v150, v151
	v_lshlrev_b32_e32 v148, 16, v210
	v_and_b32_e32 v149, 0xffff0000, v210
	v_lshlrev_b32_e32 v150, 16, v211
	v_and_b32_e32 v151, 0xffff0000, v211
	v_pk_mul_f32 v[148:149], v[64:65], v[148:149]
	v_pk_mul_f32 v[150:151], v[66:67], v[150:151]
	v_cvt_pk_bf16_f32 v210, v148, v149
	v_cvt_pk_bf16_f32 v211, v150, v151
	global_store_dwordx4 v[146:147], v[208:211], off offset:256
	s_waitcnt vmcnt(15)
	v_lshlrev_b32_e32 v148, 16, v212
	v_and_b32_e32 v149, 0xffff0000, v212
	v_lshlrev_b32_e32 v150, 16, v213
	v_and_b32_e32 v151, 0xffff0000, v213
	v_pk_mul_f32 v[148:149], v[60:61], v[148:149]
	v_pk_mul_f32 v[150:151], v[62:63], v[150:151]
	v_cvt_pk_bf16_f32 v212, v148, v149
	v_cvt_pk_bf16_f32 v213, v150, v151
	v_lshlrev_b32_e32 v148, 16, v214
	v_and_b32_e32 v149, 0xffff0000, v214
	v_lshlrev_b32_e32 v150, 16, v215
	v_and_b32_e32 v151, 0xffff0000, v215
	v_pk_mul_f32 v[148:149], v[56:57], v[148:149]
	v_pk_mul_f32 v[150:151], v[58:59], v[150:151]
	v_cvt_pk_bf16_f32 v214, v148, v149
	v_cvt_pk_bf16_f32 v215, v150, v151
	v_lshl_add_u64 v[146:147], v[206:207], 0, s[10:11]
	global_store_dwordx4 v[146:147], v[212:215], off
	s_waitcnt vmcnt(15)
	v_lshlrev_b32_e32 v148, 16, v216
	v_and_b32_e32 v149, 0xffff0000, v216
	v_lshlrev_b32_e32 v150, 16, v217
	v_and_b32_e32 v151, 0xffff0000, v217
	v_pk_mul_f32 v[148:149], v[28:29], v[148:149]
	v_pk_mul_f32 v[150:151], v[30:31], v[150:151]
	v_cvt_pk_bf16_f32 v216, v148, v149
	v_cvt_pk_bf16_f32 v217, v150, v151
	v_lshlrev_b32_e32 v148, 16, v218
	v_and_b32_e32 v149, 0xffff0000, v218
	v_lshlrev_b32_e32 v150, 16, v219
	v_and_b32_e32 v151, 0xffff0000, v219
	v_pk_mul_f32 v[148:149], v[24:25], v[148:149]
	v_pk_mul_f32 v[150:151], v[26:27], v[150:151]
	v_cvt_pk_bf16_f32 v218, v148, v149
	v_cvt_pk_bf16_f32 v219, v150, v151
	global_store_dwordx4 v[146:147], v[216:219], off offset:256
	s_waitcnt vmcnt(15)
	v_lshlrev_b32_e32 v148, 16, v220
	v_and_b32_e32 v149, 0xffff0000, v220
	v_lshlrev_b32_e32 v150, 16, v221
	v_and_b32_e32 v151, 0xffff0000, v221
	v_pk_mul_f32 v[148:149], v[52:53], v[148:149]
	v_pk_mul_f32 v[150:151], v[54:55], v[150:151]
	v_cvt_pk_bf16_f32 v220, v148, v149
	v_cvt_pk_bf16_f32 v221, v150, v151
	v_lshlrev_b32_e32 v148, 16, v222
	v_and_b32_e32 v149, 0xffff0000, v222
	v_lshlrev_b32_e32 v150, 16, v223
	v_and_b32_e32 v151, 0xffff0000, v223
	v_pk_mul_f32 v[148:149], v[48:49], v[148:149]
	v_pk_mul_f32 v[150:151], v[50:51], v[150:151]
	v_cvt_pk_bf16_f32 v222, v148, v149
	v_cvt_pk_bf16_f32 v223, v150, v151
	v_lshl_add_u64 v[146:147], v[206:207], 0, s[20:21]
	global_store_dwordx4 v[146:147], v[220:223], off
	s_waitcnt vmcnt(15)
	v_lshlrev_b32_e32 v148, 16, v224
	v_and_b32_e32 v149, 0xffff0000, v224
	v_lshlrev_b32_e32 v150, 16, v225
	v_and_b32_e32 v151, 0xffff0000, v225
	v_pk_mul_f32 v[148:149], v[20:21], v[148:149]
	v_pk_mul_f32 v[150:151], v[22:23], v[150:151]
	v_cvt_pk_bf16_f32 v224, v148, v149
	v_cvt_pk_bf16_f32 v225, v150, v151
	v_lshlrev_b32_e32 v148, 16, v226
	v_and_b32_e32 v149, 0xffff0000, v226
	v_lshlrev_b32_e32 v150, 16, v227
	v_and_b32_e32 v151, 0xffff0000, v227
	v_pk_mul_f32 v[148:149], v[16:17], v[148:149]
	v_pk_mul_f32 v[150:151], v[18:19], v[150:151]
	v_cvt_pk_bf16_f32 v226, v148, v149
	v_cvt_pk_bf16_f32 v227, v150, v151
	global_store_dwordx4 v[146:147], v[224:227], off offset:256
	s_waitcnt vmcnt(15)
	v_lshlrev_b32_e32 v148, 16, v232
	v_and_b32_e32 v149, 0xffff0000, v232
	v_lshlrev_b32_e32 v150, 16, v233
	v_and_b32_e32 v151, 0xffff0000, v233
	v_pk_mul_f32 v[148:149], v[44:45], v[148:149]
	v_pk_mul_f32 v[150:151], v[46:47], v[150:151]
	v_cvt_pk_bf16_f32 v232, v148, v149
	v_cvt_pk_bf16_f32 v233, v150, v151
	v_lshlrev_b32_e32 v148, 16, v234
	v_and_b32_e32 v149, 0xffff0000, v234
	v_lshlrev_b32_e32 v150, 16, v235
	v_and_b32_e32 v151, 0xffff0000, v235
	v_pk_mul_f32 v[148:149], v[40:41], v[148:149]
	v_pk_mul_f32 v[150:151], v[42:43], v[150:151]
	v_cvt_pk_bf16_f32 v234, v148, v149
	v_cvt_pk_bf16_f32 v235, v150, v151
	v_lshl_add_u64 v[146:147], v[206:207], 0, s[24:25]
	global_store_dwordx4 v[146:147], v[232:235], off
	s_waitcnt vmcnt(15)
	v_lshlrev_b32_e32 v148, 16, v236
	v_and_b32_e32 v149, 0xffff0000, v236
	v_lshlrev_b32_e32 v150, 16, v237
	v_and_b32_e32 v151, 0xffff0000, v237
	v_pk_mul_f32 v[148:149], v[12:13], v[148:149]
	v_pk_mul_f32 v[150:151], v[14:15], v[150:151]
	v_cvt_pk_bf16_f32 v236, v148, v149
	v_cvt_pk_bf16_f32 v237, v150, v151
	v_lshlrev_b32_e32 v148, 16, v238
	v_and_b32_e32 v149, 0xffff0000, v238
	v_lshlrev_b32_e32 v150, 16, v239
	v_and_b32_e32 v151, 0xffff0000, v239
	v_pk_mul_f32 v[148:149], v[8:9], v[148:149]
	v_pk_mul_f32 v[150:151], v[10:11], v[150:151]
	v_cvt_pk_bf16_f32 v238, v148, v149
	v_cvt_pk_bf16_f32 v239, v150, v151
	global_store_dwordx4 v[146:147], v[236:239], off offset:256
	s_waitcnt vmcnt(15)
	v_lshlrev_b32_e32 v148, 16, v240
	v_and_b32_e32 v149, 0xffff0000, v240
	v_lshlrev_b32_e32 v150, 16, v241
	v_and_b32_e32 v151, 0xffff0000, v241
	v_pk_mul_f32 v[148:149], v[36:37], v[148:149]
	v_pk_mul_f32 v[150:151], v[38:39], v[150:151]
	v_cvt_pk_bf16_f32 v240, v148, v149
	v_cvt_pk_bf16_f32 v241, v150, v151
	v_lshlrev_b32_e32 v148, 16, v242
	v_and_b32_e32 v149, 0xffff0000, v242
	v_lshlrev_b32_e32 v150, 16, v243
	v_and_b32_e32 v151, 0xffff0000, v243
	v_pk_mul_f32 v[148:149], v[32:33], v[148:149]
	v_pk_mul_f32 v[150:151], v[34:35], v[150:151]
	v_cvt_pk_bf16_f32 v242, v148, v149
	v_cvt_pk_bf16_f32 v243, v150, v151
	v_lshl_add_u64 v[146:147], v[206:207], 0, s[28:29]
	global_store_dwordx4 v[146:147], v[240:243], off
	s_waitcnt vmcnt(15)
	v_lshlrev_b32_e32 v148, 16, v244
	v_and_b32_e32 v149, 0xffff0000, v244
	v_lshlrev_b32_e32 v150, 16, v245
	v_and_b32_e32 v151, 0xffff0000, v245
	v_pk_mul_f32 v[148:149], v[4:5], v[148:149]
	v_pk_mul_f32 v[150:151], v[6:7], v[150:151]
	v_cvt_pk_bf16_f32 v244, v148, v149
	v_cvt_pk_bf16_f32 v245, v150, v151
	v_lshlrev_b32_e32 v148, 16, v246
	v_and_b32_e32 v149, 0xffff0000, v246
	v_lshlrev_b32_e32 v150, 16, v247
	v_and_b32_e32 v151, 0xffff0000, v247
	v_pk_mul_f32 v[148:149], v[0:1], v[148:149]
	v_pk_mul_f32 v[150:151], v[2:3], v[150:151]
	v_cvt_pk_bf16_f32 v246, v148, v149
	v_cvt_pk_bf16_f32 v247, v150, v151
	global_store_dwordx4 v[146:147], v[244:247], off offset:256
	s_branch .Lp3a_epi_done
.Lp3a_epi_first:
	global_load_dwordx4 v[168:171], v[196:197], off offset:2048
	global_load_dwordx4 v[172:175], v[196:197], off
	global_load_dwordx4 v[176:179], v[196:197], off offset:2304
	global_load_dwordx4 v[180:183], v[196:197], off offset:256
	v_lshl_add_u64 v[146:147], v[196:197], 0, s[60:61]
	global_load_dwordx4 v[184:187], v[146:147], off offset:2048
	global_load_dwordx4 v[188:191], v[146:147], off
	global_load_dwordx4 v[192:195], v[146:147], off offset:2304
	global_load_dwordx4 v[208:211], v[146:147], off offset:256
	v_lshl_add_u64 v[146:147], v[146:147], 0, s[60:61]
	global_load_dwordx4 v[212:215], v[146:147], off offset:2048
	global_load_dwordx4 v[216:219], v[146:147], off
	global_load_dwordx4 v[220:223], v[146:147], off offset:2304
	global_load_dwordx4 v[224:227], v[146:147], off offset:256
	v_lshl_add_u64 v[146:147], v[146:147], 0, s[60:61]
	global_load_dwordx4 v[232:235], v[146:147], off offset:2048
	global_load_dwordx4 v[236:239], v[146:147], off
	global_load_dwordx4 v[240:243], v[146:147], off offset:2304
	global_load_dwordx4 v[244:247], v[146:147], off offset:256
	s_waitcnt vmcnt(14)
	v_lshlrev_b32_e32 v148, 16, v168
	v_and_b32_e32 v149, 0xffff0000, v168
	v_lshlrev_b32_e32 v152, 16, v169
	v_and_b32_e32 v153, 0xffff0000, v169
	v_max_f32_e32 v148, 0xda24260, v148
	v_max_f32_e32 v149, 0xda24260, v149
	v_max_f32_e32 v152, 0xda24260, v152
	v_max_f32_e32 v153, 0xda24260, v153
	v_rcp_f32_e32 v148, v148
	v_rcp_f32_e32 v149, v149
	v_rcp_f32_e32 v152, v152
	v_rcp_f32_e32 v153, v153
	v_lshlrev_b32_e32 v150, 16, v172
	v_and_b32_e32 v151, 0xffff0000, v172
	v_lshlrev_b32_e32 v154, 16, v173
	v_and_b32_e32 v155, 0xffff0000, v173
	v_pk_mul_f32 v[148:149], v[148:149], v[150:151]
	v_pk_mul_f32 v[152:153], v[152:153], v[154:155]
	v_pk_mul_f32 v[124:125], v[124:125], v[148:149]
	v_pk_mul_f32 v[126:127], v[126:127], v[152:153]
	v_lshlrev_b32_e32 v148, 16, v170
	v_and_b32_e32 v149, 0xffff0000, v170
	v_lshlrev_b32_e32 v152, 16, v171
	v_and_b32_e32 v153, 0xffff0000, v171
	v_max_f32_e32 v148, 0xda24260, v148
	v_max_f32_e32 v149, 0xda24260, v149
	v_max_f32_e32 v152, 0xda24260, v152
	v_max_f32_e32 v153, 0xda24260, v153
	v_rcp_f32_e32 v148, v148
	v_rcp_f32_e32 v149, v149
	v_rcp_f32_e32 v152, v152
	v_rcp_f32_e32 v153, v153
	v_lshlrev_b32_e32 v150, 16, v174
	v_and_b32_e32 v151, 0xffff0000, v174
	v_lshlrev_b32_e32 v154, 16, v175
	v_and_b32_e32 v155, 0xffff0000, v175
	v_pk_mul_f32 v[148:149], v[148:149], v[150:151]
	v_pk_mul_f32 v[152:153], v[152:153], v[154:155]
	v_pk_mul_f32 v[120:121], v[120:121], v[148:149]
	v_pk_mul_f32 v[122:123], v[122:123], v[152:153]
	v_lshl_add_u64 v[146:147], v[196:197], 0, s[18:19]
	global_load_dwordx4 v[168:171], v[146:147], off offset:2048
	global_load_dwordx4 v[172:175], v[146:147], off
	s_waitcnt vmcnt(14)
	v_lshlrev_b32_e32 v148, 16, v176
	v_and_b32_e32 v149, 0xffff0000, v176
	v_lshlrev_b32_e32 v152, 16, v177
	v_and_b32_e32 v153, 0xffff0000, v177
	v_max_f32_e32 v148, 0xda24260, v148
	v_max_f32_e32 v149, 0xda24260, v149
	v_max_f32_e32 v152, 0xda24260, v152
	v_max_f32_e32 v153, 0xda24260, v153
	v_rcp_f32_e32 v148, v148
	v_rcp_f32_e32 v149, v149
	v_rcp_f32_e32 v152, v152
	v_rcp_f32_e32 v153, v153
	v_lshlrev_b32_e32 v150, 16, v180
	v_and_b32_e32 v151, 0xffff0000, v180
	v_lshlrev_b32_e32 v154, 16, v181
	v_and_b32_e32 v155, 0xffff0000, v181
	v_pk_mul_f32 v[148:149], v[148:149], v[150:151]
	v_pk_mul_f32 v[152:153], v[152:153], v[154:155]
	v_pk_mul_f32 v[92:93], v[92:93], v[148:149]
	v_pk_mul_f32 v[94:95], v[94:95], v[152:153]
	v_lshlrev_b32_e32 v148, 16, v178
	v_and_b32_e32 v149, 0xffff0000, v178
	v_lshlrev_b32_e32 v152, 16, v179
	v_and_b32_e32 v153, 0xffff0000, v179
	v_max_f32_e32 v148, 0xda24260, v148
	v_max_f32_e32 v149, 0xda24260, v149
	v_max_f32_e32 v152, 0xda24260, v152
	v_max_f32_e32 v153, 0xda24260, v153
	v_rcp_f32_e32 v148, v148
	v_rcp_f32_e32 v149, v149
	v_rcp_f32_e32 v152, v152
	v_rcp_f32_e32 v153, v153
	v_lshlrev_b32_e32 v150, 16, v182
	v_and_b32_e32 v151, 0xffff0000, v182
	v_lshlrev_b32_e32 v154, 16, v183
	v_and_b32_e32 v155, 0xffff0000, v183
	v_pk_mul_f32 v[148:149], v[148:149], v[150:151]
	v_pk_mul_f32 v[152:153], v[152:153], v[154:155]
	v_pk_mul_f32 v[88:89], v[88:89], v[148:149]
	v_pk_mul_f32 v[90:91], v[90:91], v[152:153]
	global_load_dwordx4 v[176:179], v[146:147], off offset:2304
	global_load_dwordx4 v[180:183], v[146:147], off offset:256
	s_waitcnt vmcnt(14)
	v_lshlrev_b32_e32 v148, 16, v184
	v_and_b32_e32 v149, 0xffff0000, v184
	v_lshlrev_b32_e32 v152, 16, v185
	v_and_b32_e32 v153, 0xffff0000, v185
	v_max_f32_e32 v148, 0xda24260, v148
	v_max_f32_e32 v149, 0xda24260, v149
	v_max_f32_e32 v152, 0xda24260, v152
	v_max_f32_e32 v153, 0xda24260, v153
	v_rcp_f32_e32 v148, v148
	v_rcp_f32_e32 v149, v149
	v_rcp_f32_e32 v152, v152
	v_rcp_f32_e32 v153, v153
	v_lshlrev_b32_e32 v150, 16, v188
	v_and_b32_e32 v151, 0xffff0000, v188
	v_lshlrev_b32_e32 v154, 16, v189
	v_and_b32_e32 v155, 0xffff0000, v189
	v_pk_mul_f32 v[148:149], v[148:149], v[150:151]
	v_pk_mul_f32 v[152:153], v[152:153], v[154:155]
	v_pk_mul_f32 v[116:117], v[116:117], v[148:149]
	v_pk_mul_f32 v[118:119], v[118:119], v[152:153]
	v_lshlrev_b32_e32 v148, 16, v186
	v_and_b32_e32 v149, 0xffff0000, v186
	v_lshlrev_b32_e32 v152, 16, v187
	v_and_b32_e32 v153, 0xffff0000, v187
	v_max_f32_e32 v148, 0xda24260, v148
	v_max_f32_e32 v149, 0xda24260, v149
	v_max_f32_e32 v152, 0xda24260, v152
	v_max_f32_e32 v153, 0xda24260, v153
	v_rcp_f32_e32 v148, v148
	v_rcp_f32_e32 v149, v149
	v_rcp_f32_e32 v152, v152
	v_rcp_f32_e32 v153, v153
	v_lshlrev_b32_e32 v150, 16, v190
	v_and_b32_e32 v151, 0xffff0000, v190
	v_lshlrev_b32_e32 v154, 16, v191
	v_and_b32_e32 v155, 0xffff0000, v191
	v_pk_mul_f32 v[148:149], v[148:149], v[150:151]
	v_pk_mul_f32 v[152:153], v[152:153], v[154:155]
	v_pk_mul_f32 v[112:113], v[112:113], v[148:149]
	v_pk_mul_f32 v[114:115], v[114:115], v[152:153]
	v_lshl_add_u64 v[146:147], v[196:197], 0, s[22:23]
	global_load_dwordx4 v[184:187], v[146:147], off offset:2048
	global_load_dwordx4 v[188:191], v[146:147], off
	s_waitcnt vmcnt(14)
	v_lshlrev_b32_e32 v148, 16, v192
	v_and_b32_e32 v149, 0xffff0000, v192
	v_lshlrev_b32_e32 v152, 16, v193
	v_and_b32_e32 v153, 0xffff0000, v193
	v_max_f32_e32 v148, 0xda24260, v148
	v_max_f32_e32 v149, 0xda24260, v149
	v_max_f32_e32 v152, 0xda24260, v152
	v_max_f32_e32 v153, 0xda24260, v153
	v_rcp_f32_e32 v148, v148
	v_rcp_f32_e32 v149, v149
	v_rcp_f32_e32 v152, v152
	v_rcp_f32_e32 v153, v153
	v_lshlrev_b32_e32 v150, 16, v208
	v_and_b32_e32 v151, 0xffff0000, v208
	v_lshlrev_b32_e32 v154, 16, v209
	v_and_b32_e32 v155, 0xffff0000, v209
	v_pk_mul_f32 v[148:149], v[148:149], v[150:151]
	v_pk_mul_f32 v[152:153], v[152:153], v[154:155]
	v_pk_mul_f32 v[84:85], v[84:85], v[148:149]
	v_pk_mul_f32 v[86:87], v[86:87], v[152:153]
	v_lshlrev_b32_e32 v148, 16, v194
	v_and_b32_e32 v149, 0xffff0000, v194
	v_lshlrev_b32_e32 v152, 16, v195
	v_and_b32_e32 v153, 0xffff0000, v195
	v_max_f32_e32 v148, 0xda24260, v148
	v_max_f32_e32 v149, 0xda24260, v149
	v_max_f32_e32 v152, 0xda24260, v152
	v_max_f32_e32 v153, 0xda24260, v153
	v_rcp_f32_e32 v148, v148
	v_rcp_f32_e32 v149, v149
	v_rcp_f32_e32 v152, v152
	v_rcp_f32_e32 v153, v153
	v_lshlrev_b32_e32 v150, 16, v210
	v_and_b32_e32 v151, 0xffff0000, v210
	v_lshlrev_b32_e32 v154, 16, v211
	v_and_b32_e32 v155, 0xffff0000, v211
	v_pk_mul_f32 v[148:149], v[148:149], v[150:151]
	v_pk_mul_f32 v[152:153], v[152:153], v[154:155]
	v_pk_mul_f32 v[80:81], v[80:81], v[148:149]
	v_pk_mul_f32 v[82:83], v[82:83], v[152:153]
	global_load_dwordx4 v[192:195], v[146:147], off offset:2304
	global_load_dwordx4 v[208:211], v[146:147], off offset:256
	s_waitcnt vmcnt(14)
	v_lshlrev_b32_e32 v148, 16, v212
	v_and_b32_e32 v149, 0xffff0000, v212
	v_lshlrev_b32_e32 v152, 16, v213
	v_and_b32_e32 v153, 0xffff0000, v213
	v_max_f32_e32 v148, 0xda24260, v148
	v_max_f32_e32 v149, 0xda24260, v149
	v_max_f32_e32 v152, 0xda24260, v152
	v_max_f32_e32 v153, 0xda24260, v153
	v_rcp_f32_e32 v148, v148
	v_rcp_f32_e32 v149, v149
	v_rcp_f32_e32 v152, v152
	v_rcp_f32_e32 v153, v153
	v_lshlrev_b32_e32 v150, 16, v216
	v_and_b32_e32 v151, 0xffff0000, v216
	v_lshlrev_b32_e32 v154, 16, v217
	v_and_b32_e32 v155, 0xffff0000, v217
	v_pk_mul_f32 v[148:149], v[148:149], v[150:151]
	v_pk_mul_f32 v[152:153], v[152:153], v[154:155]
	v_pk_mul_f32 v[108:109], v[108:109], v[148:149]
	v_pk_mul_f32 v[110:111], v[110:111], v[152:153]
	v_lshlrev_b32_e32 v148, 16, v214
	v_and_b32_e32 v149, 0xffff0000, v214
	v_lshlrev_b32_e32 v152, 16, v215
	v_and_b32_e32 v153, 0xffff0000, v215
	v_max_f32_e32 v148, 0xda24260, v148
	v_max_f32_e32 v149, 0xda24260, v149
	v_max_f32_e32 v152, 0xda24260, v152
	v_max_f32_e32 v153, 0xda24260, v153
	v_rcp_f32_e32 v148, v148
	v_rcp_f32_e32 v149, v149
	v_rcp_f32_e32 v152, v152
	v_rcp_f32_e32 v153, v153
	v_lshlrev_b32_e32 v150, 16, v218
	v_and_b32_e32 v151, 0xffff0000, v218
	v_lshlrev_b32_e32 v154, 16, v219
	v_and_b32_e32 v155, 0xffff0000, v219
	v_pk_mul_f32 v[148:149], v[148:149], v[150:151]
	v_pk_mul_f32 v[152:153], v[152:153], v[154:155]
	v_pk_mul_f32 v[104:105], v[104:105], v[148:149]
	v_pk_mul_f32 v[106:107], v[106:107], v[152:153]
	v_lshl_add_u64 v[146:147], v[196:197], 0, s[26:27]
	global_load_dwordx4 v[212:215], v[146:147], off offset:2048
	global_load_dwordx4 v[216:219], v[146:147], off
	s_waitcnt vmcnt(14)
	v_lshlrev_b32_e32 v148, 16, v220
	v_and_b32_e32 v149, 0xffff0000, v220
	v_lshlrev_b32_e32 v152, 16, v221
	v_and_b32_e32 v153, 0xffff0000, v221
	v_max_f32_e32 v148, 0xda24260, v148
	v_max_f32_e32 v149, 0xda24260, v149
	v_max_f32_e32 v152, 0xda24260, v152
	v_max_f32_e32 v153, 0xda24260, v153
	v_rcp_f32_e32 v148, v148
	v_rcp_f32_e32 v149, v149
	v_rcp_f32_e32 v152, v152
	v_rcp_f32_e32 v153, v153
	v_lshlrev_b32_e32 v150, 16, v224
	v_and_b32_e32 v151, 0xffff0000, v224
	v_lshlrev_b32_e32 v154, 16, v225
	v_and_b32_e32 v155, 0xffff0000, v225
	v_pk_mul_f32 v[148:149], v[148:149], v[150:151]
	v_pk_mul_f32 v[152:153], v[152:153], v[154:155]
	v_pk_mul_f32 v[76:77], v[76:77], v[148:149]
	v_pk_mul_f32 v[78:79], v[78:79], v[152:153]
	v_lshlrev_b32_e32 v148, 16, v222
	v_and_b32_e32 v149, 0xffff0000, v222
	v_lshlrev_b32_e32 v152, 16, v223
	v_and_b32_e32 v153, 0xffff0000, v223
	v_max_f32_e32 v148, 0xda24260, v148
	v_max_f32_e32 v149, 0xda24260, v149
	v_max_f32_e32 v152, 0xda24260, v152
	v_max_f32_e32 v153, 0xda24260, v153
	v_rcp_f32_e32 v148, v148
	v_rcp_f32_e32 v149, v149
	v_rcp_f32_e32 v152, v152
	v_rcp_f32_e32 v153, v153
	v_lshlrev_b32_e32 v150, 16, v226
	v_and_b32_e32 v151, 0xffff0000, v226
	v_lshlrev_b32_e32 v154, 16, v227
	v_and_b32_e32 v155, 0xffff0000, v227
	v_pk_mul_f32 v[148:149], v[148:149], v[150:151]
	v_pk_mul_f32 v[152:153], v[152:153], v[154:155]
	v_pk_mul_f32 v[72:73], v[72:73], v[148:149]
	v_pk_mul_f32 v[74:75], v[74:75], v[152:153]
	global_load_dwordx4 v[220:223], v[146:147], off offset:2304
	global_load_dwordx4 v[224:227], v[146:147], off offset:256
	s_waitcnt vmcnt(14)
	v_lshlrev_b32_e32 v148, 16, v232
	v_and_b32_e32 v149, 0xffff0000, v232
	v_lshlrev_b32_e32 v152, 16, v233
	v_and_b32_e32 v153, 0xffff0000, v233
	v_max_f32_e32 v148, 0xda24260, v148
	v_max_f32_e32 v149, 0xda24260, v149
	v_max_f32_e32 v152, 0xda24260, v152
	v_max_f32_e32 v153, 0xda24260, v153
	v_rcp_f32_e32 v148, v148
	v_rcp_f32_e32 v149, v149
	v_rcp_f32_e32 v152, v152
	v_rcp_f32_e32 v153, v153
	v_lshlrev_b32_e32 v150, 16, v236
	v_and_b32_e32 v151, 0xffff0000, v236
	v_lshlrev_b32_e32 v154, 16, v237
	v_and_b32_e32 v155, 0xffff0000, v237
	v_pk_mul_f32 v[148:149], v[148:149], v[150:151]
	v_pk_mul_f32 v[152:153], v[152:153], v[154:155]
	v_pk_mul_f32 v[100:101], v[100:101], v[148:149]
	v_pk_mul_f32 v[102:103], v[102:103], v[152:153]
	v_lshlrev_b32_e32 v148, 16, v234
	v_and_b32_e32 v149, 0xffff0000, v234
	v_lshlrev_b32_e32 v152, 16, v235
	v_and_b32_e32 v153, 0xffff0000, v235
	v_max_f32_e32 v148, 0xda24260, v148
	v_max_f32_e32 v149, 0xda24260, v149
	v_max_f32_e32 v152, 0xda24260, v152
	v_max_f32_e32 v153, 0xda24260, v153
	v_rcp_f32_e32 v148, v148
	v_rcp_f32_e32 v149, v149
	v_rcp_f32_e32 v152, v152
	v_rcp_f32_e32 v153, v153
	v_lshlrev_b32_e32 v150, 16, v238
	v_and_b32_e32 v151, 0xffff0000, v238
	v_lshlrev_b32_e32 v154, 16, v239
	v_and_b32_e32 v155, 0xffff0000, v239
	v_pk_mul_f32 v[148:149], v[148:149], v[150:151]
	v_pk_mul_f32 v[152:153], v[152:153], v[154:155]
	v_pk_mul_f32 v[96:97], v[96:97], v[148:149]
	v_pk_mul_f32 v[98:99], v[98:99], v[152:153]
	v_lshl_add_u64 v[146:147], v[196:197], 0, s[30:31]
	global_load_dwordx4 v[232:235], v[146:147], off offset:2048
	global_load_dwordx4 v[236:239], v[146:147], off
	s_waitcnt vmcnt(14)
	v_lshlrev_b32_e32 v148, 16, v240
	v_and_b32_e32 v149, 0xffff0000, v240
	v_lshlrev_b32_e32 v152, 16, v241
	v_and_b32_e32 v153, 0xffff0000, v241
	v_max_f32_e32 v148, 0xda24260, v148
	v_max_f32_e32 v149, 0xda24260, v149
	v_max_f32_e32 v152, 0xda24260, v152
	v_max_f32_e32 v153, 0xda24260, v153
	v_rcp_f32_e32 v148, v148
	v_rcp_f32_e32 v149, v149
	v_rcp_f32_e32 v152, v152
	v_rcp_f32_e32 v153, v153
	v_lshlrev_b32_e32 v150, 16, v244
	v_and_b32_e32 v151, 0xffff0000, v244
	v_lshlrev_b32_e32 v154, 16, v245
	v_and_b32_e32 v155, 0xffff0000, v245
	v_pk_mul_f32 v[148:149], v[148:149], v[150:151]
	v_pk_mul_f32 v[152:153], v[152:153], v[154:155]
	v_pk_mul_f32 v[68:69], v[68:69], v[148:149]
	v_pk_mul_f32 v[70:71], v[70:71], v[152:153]
	v_lshlrev_b32_e32 v148, 16, v242
	v_and_b32_e32 v149, 0xffff0000, v242
	v_lshlrev_b32_e32 v152, 16, v243
	v_and_b32_e32 v153, 0xffff0000, v243
	v_max_f32_e32 v148, 0xda24260, v148
	v_max_f32_e32 v149, 0xda24260, v149
	v_max_f32_e32 v152, 0xda24260, v152
	v_max_f32_e32 v153, 0xda24260, v153
	v_rcp_f32_e32 v148, v148
	v_rcp_f32_e32 v149, v149
	v_rcp_f32_e32 v152, v152
	v_rcp_f32_e32 v153, v153
	v_lshlrev_b32_e32 v150, 16, v246
	v_and_b32_e32 v151, 0xffff0000, v246
	v_lshlrev_b32_e32 v154, 16, v247
	v_and_b32_e32 v155, 0xffff0000, v247
	v_pk_mul_f32 v[148:149], v[148:149], v[150:151]
	v_pk_mul_f32 v[152:153], v[152:153], v[154:155]
	v_pk_mul_f32 v[64:65], v[64:65], v[148:149]
	v_pk_mul_f32 v[66:67], v[66:67], v[152:153]
	global_load_dwordx4 v[240:243], v[146:147], off offset:2304
	global_load_dwordx4 v[244:247], v[146:147], off offset:256
	s_waitcnt vmcnt(14)
	v_lshlrev_b32_e32 v148, 16, v168
	v_and_b32_e32 v149, 0xffff0000, v168
	v_lshlrev_b32_e32 v152, 16, v169
	v_and_b32_e32 v153, 0xffff0000, v169
	v_max_f32_e32 v148, 0xda24260, v148
	v_max_f32_e32 v149, 0xda24260, v149
	v_max_f32_e32 v152, 0xda24260, v152
	v_max_f32_e32 v153, 0xda24260, v153
	v_rcp_f32_e32 v148, v148
	v_rcp_f32_e32 v149, v149
	v_rcp_f32_e32 v152, v152
	v_rcp_f32_e32 v153, v153
	v_lshlrev_b32_e32 v150, 16, v172
	v_and_b32_e32 v151, 0xffff0000, v172
	v_lshlrev_b32_e32 v154, 16, v173
	v_and_b32_e32 v155, 0xffff0000, v173
	v_pk_mul_f32 v[148:149], v[148:149], v[150:151]
	v_pk_mul_f32 v[152:153], v[152:153], v[154:155]
	v_pk_mul_f32 v[60:61], v[60:61], v[148:149]
	v_pk_mul_f32 v[62:63], v[62:63], v[152:153]
	v_lshlrev_b32_e32 v148, 16, v170
	v_and_b32_e32 v149, 0xffff0000, v170
	v_lshlrev_b32_e32 v152, 16, v171
	v_and_b32_e32 v153, 0xffff0000, v171
	v_max_f32_e32 v148, 0xda24260, v148
	v_max_f32_e32 v149, 0xda24260, v149
	v_max_f32_e32 v152, 0xda24260, v152
	v_max_f32_e32 v153, 0xda24260, v153
	v_rcp_f32_e32 v148, v148
	v_rcp_f32_e32 v149, v149
	v_rcp_f32_e32 v152, v152
	v_rcp_f32_e32 v153, v153
	v_lshlrev_b32_e32 v150, 16, v174
	v_and_b32_e32 v151, 0xffff0000, v174
	v_lshlrev_b32_e32 v154, 16, v175
	v_and_b32_e32 v155, 0xffff0000, v175
	v_pk_mul_f32 v[148:149], v[148:149], v[150:151]
	v_pk_mul_f32 v[152:153], v[152:153], v[154:155]
	v_pk_mul_f32 v[56:57], v[56:57], v[148:149]
	v_pk_mul_f32 v[58:59], v[58:59], v[152:153]
	s_waitcnt vmcnt(12)
	v_lshlrev_b32_e32 v148, 16, v176
	v_and_b32_e32 v149, 0xffff0000, v176
	v_lshlrev_b32_e32 v152, 16, v177
	v_and_b32_e32 v153, 0xffff0000, v177
	v_max_f32_e32 v148, 0xda24260, v148
	v_max_f32_e32 v149, 0xda24260, v149
	v_max_f32_e32 v152, 0xda24260, v152
	v_max_f32_e32 v153, 0xda24260, v153
	v_rcp_f32_e32 v148, v148
	v_rcp_f32_e32 v149, v149
	v_rcp_f32_e32 v152, v152
	v_rcp_f32_e32 v153, v153
	v_lshlrev_b32_e32 v150, 16, v180
	v_and_b32_e32 v151, 0xffff0000, v180
	v_lshlrev_b32_e32 v154, 16, v181
	v_and_b32_e32 v155, 0xffff0000, v181
	v_pk_mul_f32 v[148:149], v[148:149], v[150:151]
	v_pk_mul_f32 v[152:153], v[152:153], v[154:155]
	v_pk_mul_f32 v[28:29], v[28:29], v[148:149]
	v_pk_mul_f32 v[30:31], v[30:31], v[152:153]
	v_lshlrev_b32_e32 v148, 16, v178
	v_and_b32_e32 v149, 0xffff0000, v178
	v_lshlrev_b32_e32 v152, 16, v179
	v_and_b32_e32 v153, 0xffff0000, v179
	v_max_f32_e32 v148, 0xda24260, v148
	v_max_f32_e32 v149, 0xda24260, v149
	v_max_f32_e32 v152, 0xda24260, v152
	v_max_f32_e32 v153, 0xda24260, v153
	v_rcp_f32_e32 v148, v148
	v_rcp_f32_e32 v149, v149
	v_rcp_f32_e32 v152, v152
	v_rcp_f32_e32 v153, v153
	v_lshlrev_b32_e32 v150, 16, v182
	v_and_b32_e32 v151, 0xffff0000, v182
	v_lshlrev_b32_e32 v154, 16, v183
	v_and_b32_e32 v155, 0xffff0000, v183
	v_pk_mul_f32 v[148:149], v[148:149], v[150:151]
	v_pk_mul_f32 v[152:153], v[152:153], v[154:155]
	v_pk_mul_f32 v[24:25], v[24:25], v[148:149]
	v_pk_mul_f32 v[26:27], v[26:27], v[152:153]
	s_waitcnt vmcnt(10)
	v_lshlrev_b32_e32 v148, 16, v184
	v_and_b32_e32 v149, 0xffff0000, v184
	v_lshlrev_b32_e32 v152, 16, v185
	v_and_b32_e32 v153, 0xffff0000, v185
	v_max_f32_e32 v148, 0xda24260, v148
	v_max_f32_e32 v149, 0xda24260, v149
	v_max_f32_e32 v152, 0xda24260, v152
	v_max_f32_e32 v153, 0xda24260, v153
	v_rcp_f32_e32 v148, v148
	v_rcp_f32_e32 v149, v149
	v_rcp_f32_e32 v152, v152
	v_rcp_f32_e32 v153, v153
	v_lshlrev_b32_e32 v150, 16, v188
	v_and_b32_e32 v151, 0xffff0000, v188
	v_lshlrev_b32_e32 v154, 16, v189
	v_and_b32_e32 v155, 0xffff0000, v189
	v_pk_mul_f32 v[148:149], v[148:149], v[150:151]
	v_pk_mul_f32 v[152:153], v[152:153], v[154:155]
	v_pk_mul_f32 v[52:53], v[52:53], v[148:149]
	v_pk_mul_f32 v[54:55], v[54:55], v[152:153]
	v_lshlrev_b32_e32 v148, 16, v186
	v_and_b32_e32 v149, 0xffff0000, v186
	v_lshlrev_b32_e32 v152, 16, v187
	v_and_b32_e32 v153, 0xffff0000, v187
	v_max_f32_e32 v148, 0xda24260, v148
	v_max_f32_e32 v149, 0xda24260, v149
	v_max_f32_e32 v152, 0xda24260, v152
	v_max_f32_e32 v153, 0xda24260, v153
	v_rcp_f32_e32 v148, v148
	v_rcp_f32_e32 v149, v149
	v_rcp_f32_e32 v152, v152
	v_rcp_f32_e32 v153, v153
	v_lshlrev_b32_e32 v150, 16, v190
	v_and_b32_e32 v151, 0xffff0000, v190
	v_lshlrev_b32_e32 v154, 16, v191
	v_and_b32_e32 v155, 0xffff0000, v191
	v_pk_mul_f32 v[148:149], v[148:149], v[150:151]
	v_pk_mul_f32 v[152:153], v[152:153], v[154:155]
	v_pk_mul_f32 v[48:49], v[48:49], v[148:149]
	v_pk_mul_f32 v[50:51], v[50:51], v[152:153]
	s_waitcnt vmcnt(8)
	v_lshlrev_b32_e32 v148, 16, v192
	v_and_b32_e32 v149, 0xffff0000, v192
	v_lshlrev_b32_e32 v152, 16, v193
	v_and_b32_e32 v153, 0xffff0000, v193
	v_max_f32_e32 v148, 0xda24260, v148
	v_max_f32_e32 v149, 0xda24260, v149
	v_max_f32_e32 v152, 0xda24260, v152
	v_max_f32_e32 v153, 0xda24260, v153
	v_rcp_f32_e32 v148, v148
	v_rcp_f32_e32 v149, v149
	v_rcp_f32_e32 v152, v152
	v_rcp_f32_e32 v153, v153
	v_lshlrev_b32_e32 v150, 16, v208
	v_and_b32_e32 v151, 0xffff0000, v208
	v_lshlrev_b32_e32 v154, 16, v209
	v_and_b32_e32 v155, 0xffff0000, v209
	v_pk_mul_f32 v[148:149], v[148:149], v[150:151]
	v_pk_mul_f32 v[152:153], v[152:153], v[154:155]
	v_pk_mul_f32 v[20:21], v[20:21], v[148:149]
	v_pk_mul_f32 v[22:23], v[22:23], v[152:153]
	v_lshlrev_b32_e32 v148, 16, v194
	v_and_b32_e32 v149, 0xffff0000, v194
	v_lshlrev_b32_e32 v152, 16, v195
	v_and_b32_e32 v153, 0xffff0000, v195
	v_max_f32_e32 v148, 0xda24260, v148
	v_max_f32_e32 v149, 0xda24260, v149
	v_max_f32_e32 v152, 0xda24260, v152
	v_max_f32_e32 v153, 0xda24260, v153
	v_rcp_f32_e32 v148, v148
	v_rcp_f32_e32 v149, v149
	v_rcp_f32_e32 v152, v152
	v_rcp_f32_e32 v153, v153
	v_lshlrev_b32_e32 v150, 16, v210
	v_and_b32_e32 v151, 0xffff0000, v210
	v_lshlrev_b32_e32 v154, 16, v211
	v_and_b32_e32 v155, 0xffff0000, v211
	v_pk_mul_f32 v[148:149], v[148:149], v[150:151]
	v_pk_mul_f32 v[152:153], v[152:153], v[154:155]
	v_pk_mul_f32 v[16:17], v[16:17], v[148:149]
	v_pk_mul_f32 v[18:19], v[18:19], v[152:153]
	s_waitcnt vmcnt(6)
	v_lshlrev_b32_e32 v148, 16, v212
	v_and_b32_e32 v149, 0xffff0000, v212
	v_lshlrev_b32_e32 v152, 16, v213
	v_and_b32_e32 v153, 0xffff0000, v213
	v_max_f32_e32 v148, 0xda24260, v148
	v_max_f32_e32 v149, 0xda24260, v149
	v_max_f32_e32 v152, 0xda24260, v152
	v_max_f32_e32 v153, 0xda24260, v153
	v_rcp_f32_e32 v148, v148
	v_rcp_f32_e32 v149, v149
	v_rcp_f32_e32 v152, v152
	v_rcp_f32_e32 v153, v153
	v_lshlrev_b32_e32 v150, 16, v216
	v_and_b32_e32 v151, 0xffff0000, v216
	v_lshlrev_b32_e32 v154, 16, v217
	v_and_b32_e32 v155, 0xffff0000, v217
	v_pk_mul_f32 v[148:149], v[148:149], v[150:151]
	v_pk_mul_f32 v[152:153], v[152:153], v[154:155]
	v_pk_mul_f32 v[44:45], v[44:45], v[148:149]
	v_pk_mul_f32 v[46:47], v[46:47], v[152:153]
	v_lshlrev_b32_e32 v148, 16, v214
	v_and_b32_e32 v149, 0xffff0000, v214
	v_lshlrev_b32_e32 v152, 16, v215
	v_and_b32_e32 v153, 0xffff0000, v215
	v_max_f32_e32 v148, 0xda24260, v148
	v_max_f32_e32 v149, 0xda24260, v149
	v_max_f32_e32 v152, 0xda24260, v152
	v_max_f32_e32 v153, 0xda24260, v153
	v_rcp_f32_e32 v148, v148
	v_rcp_f32_e32 v149, v149
	v_rcp_f32_e32 v152, v152
	v_rcp_f32_e32 v153, v153
	v_lshlrev_b32_e32 v150, 16, v218
	v_and_b32_e32 v151, 0xffff0000, v218
	v_lshlrev_b32_e32 v154, 16, v219
	v_and_b32_e32 v155, 0xffff0000, v219
	v_pk_mul_f32 v[148:149], v[148:149], v[150:151]
	v_pk_mul_f32 v[152:153], v[152:153], v[154:155]
	v_pk_mul_f32 v[40:41], v[40:41], v[148:149]
	v_pk_mul_f32 v[42:43], v[42:43], v[152:153]
	s_waitcnt vmcnt(4)
	v_lshlrev_b32_e32 v148, 16, v220
	v_and_b32_e32 v149, 0xffff0000, v220
	v_lshlrev_b32_e32 v152, 16, v221
	v_and_b32_e32 v153, 0xffff0000, v221
	v_max_f32_e32 v148, 0xda24260, v148
	v_max_f32_e32 v149, 0xda24260, v149
	v_max_f32_e32 v152, 0xda24260, v152
	v_max_f32_e32 v153, 0xda24260, v153
	v_rcp_f32_e32 v148, v148
	v_rcp_f32_e32 v149, v149
	v_rcp_f32_e32 v152, v152
	v_rcp_f32_e32 v153, v153
	v_lshlrev_b32_e32 v150, 16, v224
	v_and_b32_e32 v151, 0xffff0000, v224
	v_lshlrev_b32_e32 v154, 16, v225
	v_and_b32_e32 v155, 0xffff0000, v225
	v_pk_mul_f32 v[148:149], v[148:149], v[150:151]
	v_pk_mul_f32 v[152:153], v[152:153], v[154:155]
	v_pk_mul_f32 v[12:13], v[12:13], v[148:149]
	v_pk_mul_f32 v[14:15], v[14:15], v[152:153]
	v_lshlrev_b32_e32 v148, 16, v222
	v_and_b32_e32 v149, 0xffff0000, v222
	v_lshlrev_b32_e32 v152, 16, v223
	v_and_b32_e32 v153, 0xffff0000, v223
	v_max_f32_e32 v148, 0xda24260, v148
	v_max_f32_e32 v149, 0xda24260, v149
	v_max_f32_e32 v152, 0xda24260, v152
	v_max_f32_e32 v153, 0xda24260, v153
	v_rcp_f32_e32 v148, v148
	v_rcp_f32_e32 v149, v149
	v_rcp_f32_e32 v152, v152
	v_rcp_f32_e32 v153, v153
	v_lshlrev_b32_e32 v150, 16, v226
	v_and_b32_e32 v151, 0xffff0000, v226
	v_lshlrev_b32_e32 v154, 16, v227
	v_and_b32_e32 v155, 0xffff0000, v227
	v_pk_mul_f32 v[148:149], v[148:149], v[150:151]
	v_pk_mul_f32 v[152:153], v[152:153], v[154:155]
	v_pk_mul_f32 v[8:9], v[8:9], v[148:149]
	v_pk_mul_f32 v[10:11], v[10:11], v[152:153]
	s_waitcnt vmcnt(2)
	v_lshlrev_b32_e32 v148, 16, v232
	v_and_b32_e32 v149, 0xffff0000, v232
	v_lshlrev_b32_e32 v152, 16, v233
	v_and_b32_e32 v153, 0xffff0000, v233
	v_max_f32_e32 v148, 0xda24260, v148
	v_max_f32_e32 v149, 0xda24260, v149
	v_max_f32_e32 v152, 0xda24260, v152
	v_max_f32_e32 v153, 0xda24260, v153
	v_rcp_f32_e32 v148, v148
	v_rcp_f32_e32 v149, v149
	v_rcp_f32_e32 v152, v152
	v_rcp_f32_e32 v153, v153
	v_lshlrev_b32_e32 v150, 16, v236
	v_and_b32_e32 v151, 0xffff0000, v236
	v_lshlrev_b32_e32 v154, 16, v237
	v_and_b32_e32 v155, 0xffff0000, v237
	v_pk_mul_f32 v[148:149], v[148:149], v[150:151]
	v_pk_mul_f32 v[152:153], v[152:153], v[154:155]
	v_pk_mul_f32 v[36:37], v[36:37], v[148:149]
	v_pk_mul_f32 v[38:39], v[38:39], v[152:153]
	v_lshlrev_b32_e32 v148, 16, v234
	v_and_b32_e32 v149, 0xffff0000, v234
	v_lshlrev_b32_e32 v152, 16, v235
	v_and_b32_e32 v153, 0xffff0000, v235
	v_max_f32_e32 v148, 0xda24260, v148
	v_max_f32_e32 v149, 0xda24260, v149
	v_max_f32_e32 v152, 0xda24260, v152
	v_max_f32_e32 v153, 0xda24260, v153
	v_rcp_f32_e32 v148, v148
	v_rcp_f32_e32 v149, v149
	v_rcp_f32_e32 v152, v152
	v_rcp_f32_e32 v153, v153
	v_lshlrev_b32_e32 v150, 16, v238
	v_and_b32_e32 v151, 0xffff0000, v238
	v_lshlrev_b32_e32 v154, 16, v239
	v_and_b32_e32 v155, 0xffff0000, v239
	v_pk_mul_f32 v[148:149], v[148:149], v[150:151]
	v_pk_mul_f32 v[152:153], v[152:153], v[154:155]
	v_pk_mul_f32 v[32:33], v[32:33], v[148:149]
	v_pk_mul_f32 v[34:35], v[34:35], v[152:153]
	s_waitcnt vmcnt(0)
	v_lshlrev_b32_e32 v148, 16, v240
	v_and_b32_e32 v149, 0xffff0000, v240
	v_lshlrev_b32_e32 v152, 16, v241
	v_and_b32_e32 v153, 0xffff0000, v241
	v_max_f32_e32 v148, 0xda24260, v148
	v_max_f32_e32 v149, 0xda24260, v149
	v_max_f32_e32 v152, 0xda24260, v152
	v_max_f32_e32 v153, 0xda24260, v153
	v_rcp_f32_e32 v148, v148
	v_rcp_f32_e32 v149, v149
	v_rcp_f32_e32 v152, v152
	v_rcp_f32_e32 v153, v153
	v_lshlrev_b32_e32 v150, 16, v244
	v_and_b32_e32 v151, 0xffff0000, v244
	v_lshlrev_b32_e32 v154, 16, v245
	v_and_b32_e32 v155, 0xffff0000, v245
	v_pk_mul_f32 v[148:149], v[148:149], v[150:151]
	v_pk_mul_f32 v[152:153], v[152:153], v[154:155]
	v_pk_mul_f32 v[4:5], v[4:5], v[148:149]
	v_pk_mul_f32 v[6:7], v[6:7], v[152:153]
	v_lshlrev_b32_e32 v148, 16, v242
	v_and_b32_e32 v149, 0xffff0000, v242
	v_lshlrev_b32_e32 v152, 16, v243
	v_and_b32_e32 v153, 0xffff0000, v243
	v_max_f32_e32 v148, 0xda24260, v148
	v_max_f32_e32 v149, 0xda24260, v149
	v_max_f32_e32 v152, 0xda24260, v152
	v_max_f32_e32 v153, 0xda24260, v153
	v_rcp_f32_e32 v148, v148
	v_rcp_f32_e32 v149, v149
	v_rcp_f32_e32 v152, v152
	v_rcp_f32_e32 v153, v153
	v_lshlrev_b32_e32 v150, 16, v246
	v_and_b32_e32 v151, 0xffff0000, v246
	v_lshlrev_b32_e32 v154, 16, v247
	v_and_b32_e32 v155, 0xffff0000, v247
	v_pk_mul_f32 v[148:149], v[148:149], v[150:151]
	v_pk_mul_f32 v[152:153], v[152:153], v[154:155]
	v_pk_mul_f32 v[0:1], v[0:1], v[148:149]
	v_pk_mul_f32 v[2:3], v[2:3], v[152:153]
.Lp3a_epi_done:
	s_not_b64 s[8:9], s[62:63]

.LBB0_728:
	v_lshl_add_u64 v[28:29], s[44:45], 0, v[18:19]
	global_load_dword v48, v[28:29], off
	s_ashr_i32 s12, s2, 11
	s_mulk_i32 s12, 0xc00
	s_ashr_i32 s13, s12, 31
	s_lshl_b64 s[12:13], s[12:13], 2
	s_add_u32 s12, s44, s12
	s_addc_u32 s13, s45, s13
	s_add_u32 s12, s12, 0x2000
	s_addc_u32 s13, s13, 0
	v_lshl_add_u64 v[32:33], s[44:45], 0, v[20:21]
	v_add_co_u32_e32 v38, vcc, s14, v32
	s_nop 1
	v_addc_co_u32_e32 v39, vcc, 0, v33, vcc
	global_load_dwordx2 v[52:53], v[38:39], off
	global_load_dwordx2 v[54:55], v[38:39], off offset:512
	global_load_dwordx2 v[56:57], v[38:39], off offset:1024
	global_load_dwordx2 v[58:59], v[38:39], off offset:1536
	v_lshl_add_u64 v[36:37], s[10:11], 0, v[16:17]
	global_load_dwordx4 v[60:63], v[36:37], off
	global_load_dwordx4 v[64:67], v[36:37], off offset:1024
	global_load_dwordx4 v[68:71], v[36:37], off offset:2048
	global_load_dwordx4 v[72:75], v[36:37], off offset:3072
	global_load_dwordx4 v[76:79], v23, s[12:13]
	global_load_dwordx4 v[80:83], v24, s[12:13]
	global_load_dwordx4 v[84:87], v25, s[12:13]
	global_load_dwordx4 v[88:91], v26, s[12:13]
	v_lshl_add_u64 v[50:51], s[4:5], 0, v[16:17]
	s_add_i32 s2, s2, s48
	s_add_u32 s4, s4, s6
	s_addc_u32 s5, s5, s7
	s_add_u32 s10, s10, s6
	s_addc_u32 s11, s11, s7
	v_lshl_add_u64 v[18:19], v[18:19], 0, s[0:1]
	v_lshl_add_u64 v[20:21], v[20:21], 0, s[8:9]
	s_cmp_lt_i32 s2, 0x8000
	s_cbranch_scc0 .Lp4_final_a
	v_lshl_add_u64 v[28:29], s[44:45], 0, v[18:19]
	global_load_dword v96, v[28:29], off
	s_ashr_i32 s12, s2, 11
	s_mulk_i32 s12, 0xc00
	s_ashr_i32 s13, s12, 31
	s_lshl_b64 s[12:13], s[12:13], 2
	s_add_u32 s12, s44, s12
	s_addc_u32 s13, s45, s13
	s_add_u32 s12, s12, 0x2000
	s_addc_u32 s13, s13, 0
	v_lshl_add_u64 v[32:33], s[44:45], 0, v[20:21]
	v_add_co_u32_e32 v38, vcc, s14, v32
	s_nop 1
	v_addc_co_u32_e32 v39, vcc, 0, v33, vcc
	global_load_dwordx2 v[100:101], v[38:39], off
	global_load_dwordx2 v[102:103], v[38:39], off offset:512
	global_load_dwordx2 v[104:105], v[38:39], off offset:1024
	global_load_dwordx2 v[106:107], v[38:39], off offset:1536
	v_lshl_add_u64 v[36:37], s[10:11], 0, v[16:17]
	global_load_dwordx4 v[108:111], v[36:37], off
	global_load_dwordx4 v[112:115], v[36:37], off offset:1024
	global_load_dwordx4 v[116:119], v[36:37], off offset:2048
	global_load_dwordx4 v[120:123], v[36:37], off offset:3072
	global_load_dwordx4 v[124:127], v23, s[12:13]
	global_load_dwordx4 v[128:131], v24, s[12:13]
	global_load_dwordx4 v[132:135], v25, s[12:13]
	global_load_dwordx4 v[136:139], v26, s[12:13]
	v_lshl_add_u64 v[98:99], s[4:5], 0, v[16:17]
	s_add_i32 s2, s2, s48
	s_add_u32 s4, s4, s6
	s_addc_u32 s5, s5, s7
	s_add_u32 s10, s10, s6
	s_addc_u32 s11, s11, s7
	v_lshl_add_u64 v[18:19], v[18:19], 0, s[0:1]
	v_lshl_add_u64 v[20:21], v[20:21], 0, s[8:9]
	s_waitcnt vmcnt(13)
.Lp4_loop:
	ds_bpermute_b32 v46, v199, v48
	s_waitcnt lgkmcnt(0)
	v_add_f32_e32 v27, v48, v46
	ds_bpermute_b32 v46, v200, v27
	s_waitcnt lgkmcnt(0)
	v_add_f32_e32 v27, v27, v46
	ds_bpermute_b32 v46, v201, v27
	s_waitcnt lgkmcnt(0)
	v_add_f32_e32 v27, v27, v46
	ds_bpermute_b32 v46, v202, v27
	s_waitcnt lgkmcnt(0)
	v_add_f32_e32 v27, v27, v46
	v_fmamk_f32 v27, v27, 0x3a800000, v22
	v_mul_f32_e32 v46, 0x4b800000, v27
	v_cmp_gt_f32_e32 vcc, s3, v27
	s_nop 1
	v_cndmask_b32_e32 v27, v27, v46, vcc
	v_rsq_f32_e32 v27, v27
	s_nop 0
	v_mul_f32_e32 v46, 0x45800000, v27
	v_cndmask_b32_e32 v46, v27, v46, vcc
	v_lshlrev_b32_e32 v44, 16, v52
	v_and_b32_e32 v45, 0xffff0000, v52
	v_lshlrev_b32_e32 v40, 16, v53
	v_and_b32_e32 v41, 0xffff0000, v53
	v_pk_mul_f32 v[40:41], v[46:47], v[40:41] op_sel_hi:[0,1]
	v_pk_mul_f32 v[44:45], v[46:47], v[44:45] op_sel_hi:[0,1]
	v_pk_mul_f32 v[44:45], v[0:1], v[44:45]
	v_pk_mul_f32 v[40:41], v[2:3], v[40:41]
	v_pk_fma_f32 v[60:61], v[76:77], v[44:45], v[60:61]
	v_pk_fma_f32 v[62:63], v[78:79], v[40:41], v[62:63]
	global_store_dwordx4 v[50:51], v[60:63], off
	v_lshlrev_b32_e32 v44, 16, v54
	v_and_b32_e32 v45, 0xffff0000, v54
	v_lshlrev_b32_e32 v40, 16, v55
	v_and_b32_e32 v41, 0xffff0000, v55
	v_pk_mul_f32 v[40:41], v[46:47], v[40:41] op_sel_hi:[0,1]
	v_pk_mul_f32 v[44:45], v[46:47], v[44:45] op_sel_hi:[0,1]
	v_pk_mul_f32 v[44:45], v[4:5], v[44:45]
	v_pk_mul_f32 v[40:41], v[6:7], v[40:41]
	v_pk_fma_f32 v[64:65], v[80:81], v[44:45], v[64:65]
	v_pk_fma_f32 v[66:67], v[82:83], v[40:41], v[66:67]
	global_store_dwordx4 v[50:51], v[64:67], off offset:1024
	v_lshlrev_b32_e32 v44, 16, v56
	v_and_b32_e32 v45, 0xffff0000, v56
	v_lshlrev_b32_e32 v40, 16, v57
	v_and_b32_e32 v41, 0xffff0000, v57
	v_pk_mul_f32 v[40:41], v[46:47], v[40:41] op_sel_hi:[0,1]
	v_pk_mul_f32 v[44:45], v[46:47], v[44:45] op_sel_hi:[0,1]
	v_pk_mul_f32 v[44:45], v[8:9], v[44:45]
	v_pk_mul_f32 v[40:41], v[10:11], v[40:41]
	v_pk_fma_f32 v[68:69], v[84:85], v[44:45], v[68:69]
	v_pk_fma_f32 v[70:71], v[86:87], v[40:41], v[70:71]
	global_store_dwordx4 v[50:51], v[68:71], off offset:2048
	v_lshlrev_b32_e32 v44, 16, v58
	v_and_b32_e32 v45, 0xffff0000, v58
	v_lshlrev_b32_e32 v40, 16, v59
	v_and_b32_e32 v41, 0xffff0000, v59
	v_pk_mul_f32 v[40:41], v[46:47], v[40:41] op_sel_hi:[0,1]
	v_pk_mul_f32 v[44:45], v[46:47], v[44:45] op_sel_hi:[0,1]
	v_pk_mul_f32 v[44:45], v[12:13], v[44:45]
	v_pk_mul_f32 v[40:41], v[14:15], v[40:41]
	v_pk_fma_f32 v[72:73], v[88:89], v[44:45], v[72:73]
	v_pk_fma_f32 v[74:75], v[90:91], v[40:41], v[74:75]
	global_store_dwordx4 v[50:51], v[72:75], off offset:3072
	s_cmp_lt_i32 s2, 0x8000
	s_cbranch_scc0 .Lp4_final_b
	v_lshl_add_u64 v[28:29], s[44:45], 0, v[18:19]
	global_load_dword v48, v[28:29], off
	s_ashr_i32 s12, s2, 11
	s_mulk_i32 s12, 0xc00
	s_ashr_i32 s13, s12, 31
	s_lshl_b64 s[12:13], s[12:13], 2
	s_add_u32 s12, s44, s12
	s_addc_u32 s13, s45, s13
	s_add_u32 s12, s12, 0x2000
	s_addc_u32 s13, s13, 0
	v_lshl_add_u64 v[32:33], s[44:45], 0, v[20:21]
	v_add_co_u32_e32 v38, vcc, s14, v32
	s_nop 1
	v_addc_co_u32_e32 v39, vcc, 0, v33, vcc
	global_load_dwordx2 v[52:53], v[38:39], off
	global_load_dwordx2 v[54:55], v[38:39], off offset:512
	global_load_dwordx2 v[56:57], v[38:39], off offset:1024
	global_load_dwordx2 v[58:59], v[38:39], off offset:1536
	v_lshl_add_u64 v[36:37], s[10:11], 0, v[16:17]
	global_load_dwordx4 v[60:63], v[36:37], off
	global_load_dwordx4 v[64:67], v[36:37], off offset:1024
	global_load_dwordx4 v[68:71], v[36:37], off offset:2048
	global_load_dwordx4 v[72:75], v[36:37], off offset:3072
	global_load_dwordx4 v[76:79], v23, s[12:13]
	global_load_dwordx4 v[80:83], v24, s[12:13]
	global_load_dwordx4 v[84:87], v25, s[12:13]
	global_load_dwordx4 v[88:91], v26, s[12:13]
	v_lshl_add_u64 v[50:51], s[4:5], 0, v[16:17]
	s_add_i32 s2, s2, s48
	s_add_u32 s4, s4, s6
	s_addc_u32 s5, s5, s7
	s_add_u32 s10, s10, s6
	s_addc_u32 s11, s11, s7
	v_lshl_add_u64 v[18:19], v[18:19], 0, s[0:1]
	v_lshl_add_u64 v[20:21], v[20:21], 0, s[8:9]
	s_waitcnt vmcnt(17)
	ds_bpermute_b32 v46, v199, v96
	s_waitcnt lgkmcnt(0)
	v_add_f32_e32 v27, v96, v46
	ds_bpermute_b32 v46, v200, v27
	s_waitcnt lgkmcnt(0)
	v_add_f32_e32 v27, v27, v46
	ds_bpermute_b32 v46, v201, v27
	s_waitcnt lgkmcnt(0)
	v_add_f32_e32 v27, v27, v46
	ds_bpermute_b32 v46, v202, v27
	s_waitcnt lgkmcnt(0)
	v_add_f32_e32 v27, v27, v46
	v_fmamk_f32 v27, v27, 0x3a800000, v22
	v_mul_f32_e32 v46, 0x4b800000, v27
	v_cmp_gt_f32_e32 vcc, s3, v27
	s_nop 1
	v_cndmask_b32_e32 v27, v27, v46, vcc
	v_rsq_f32_e32 v27, v27
	s_nop 0
	v_mul_f32_e32 v46, 0x45800000, v27
	v_cndmask_b32_e32 v46, v27, v46, vcc
	v_lshlrev_b32_e32 v44, 16, v100
	v_and_b32_e32 v45, 0xffff0000, v100
	v_lshlrev_b32_e32 v40, 16, v101
	v_and_b32_e32 v41, 0xffff0000, v101
	v_pk_mul_f32 v[40:41], v[46:47], v[40:41] op_sel_hi:[0,1]
	v_pk_mul_f32 v[44:45], v[46:47], v[44:45] op_sel_hi:[0,1]
	v_pk_mul_f32 v[44:45], v[0:1], v[44:45]
	v_pk_mul_f32 v[40:41], v[2:3], v[40:41]
	v_pk_fma_f32 v[108:109], v[124:125], v[44:45], v[108:109]
	v_pk_fma_f32 v[110:111], v[126:127], v[40:41], v[110:111]
	global_store_dwordx4 v[98:99], v[108:111], off
	v_lshlrev_b32_e32 v44, 16, v102
	v_and_b32_e32 v45, 0xffff0000, v102
	v_lshlrev_b32_e32 v40, 16, v103
	v_and_b32_e32 v41, 0xffff0000, v103
	v_pk_mul_f32 v[40:41], v[46:47], v[40:41] op_sel_hi:[0,1]
	v_pk_mul_f32 v[44:45], v[46:47], v[44:45] op_sel_hi:[0,1]
	v_pk_mul_f32 v[44:45], v[4:5], v[44:45]
	v_pk_mul_f32 v[40:41], v[6:7], v[40:41]
	v_pk_fma_f32 v[112:113], v[128:129], v[44:45], v[112:113]
	v_pk_fma_f32 v[114:115], v[130:131], v[40:41], v[114:115]
	global_store_dwordx4 v[98:99], v[112:115], off offset:1024
	v_lshlrev_b32_e32 v44, 16, v104
	v_and_b32_e32 v45, 0xffff0000, v104
	v_lshlrev_b32_e32 v40, 16, v105
	v_and_b32_e32 v41, 0xffff0000, v105
	v_pk_mul_f32 v[40:41], v[46:47], v[40:41] op_sel_hi:[0,1]
	v_pk_mul_f32 v[44:45], v[46:47], v[44:45] op_sel_hi:[0,1]
	v_pk_mul_f32 v[44:45], v[8:9], v[44:45]
	v_pk_mul_f32 v[40:41], v[10:11], v[40:41]
	v_pk_fma_f32 v[116:117], v[132:133], v[44:45], v[116:117]
	v_pk_fma_f32 v[118:119], v[134:135], v[40:41], v[118:119]
	global_store_dwordx4 v[98:99], v[116:119], off offset:2048
	v_lshlrev_b32_e32 v44, 16, v106
	v_and_b32_e32 v45, 0xffff0000, v106
	v_lshlrev_b32_e32 v40, 16, v107
	v_and_b32_e32 v41, 0xffff0000, v107
	v_pk_mul_f32 v[40:41], v[46:47], v[40:41] op_sel_hi:[0,1]
	v_pk_mul_f32 v[44:45], v[46:47], v[44:45] op_sel_hi:[0,1]
	v_pk_mul_f32 v[44:45], v[12:13], v[44:45]
	v_pk_mul_f32 v[40:41], v[14:15], v[40:41]
	v_pk_fma_f32 v[120:121], v[136:137], v[44:45], v[120:121]
	v_pk_fma_f32 v[122:123], v[138:139], v[40:41], v[122:123]
	global_store_dwordx4 v[98:99], v[120:123], off offset:3072
	s_cmp_lt_i32 s2, 0x8000
	s_cbranch_scc0 .Lp4_final_a
	v_lshl_add_u64 v[28:29], s[44:45], 0, v[18:19]
	global_load_dword v96, v[28:29], off
	s_ashr_i32 s12, s2, 11
	s_mulk_i32 s12, 0xc00
	s_ashr_i32 s13, s12, 31
	s_lshl_b64 s[12:13], s[12:13], 2
	s_add_u32 s12, s44, s12
	s_addc_u32 s13, s45, s13
	s_add_u32 s12, s12, 0x2000
	s_addc_u32 s13, s13, 0
	v_lshl_add_u64 v[32:33], s[44:45], 0, v[20:21]
	v_add_co_u32_e32 v38, vcc, s14, v32
	s_nop 1
	v_addc_co_u32_e32 v39, vcc, 0, v33, vcc
	global_load_dwordx2 v[100:101], v[38:39], off
	global_load_dwordx2 v[102:103], v[38:39], off offset:512
	global_load_dwordx2 v[104:105], v[38:39], off offset:1024
	global_load_dwordx2 v[106:107], v[38:39], off offset:1536
	v_lshl_add_u64 v[36:37], s[10:11], 0, v[16:17]
	global_load_dwordx4 v[108:111], v[36:37], off
	global_load_dwordx4 v[112:115], v[36:37], off offset:1024
	global_load_dwordx4 v[116:119], v[36:37], off offset:2048
	global_load_dwordx4 v[120:123], v[36:37], off offset:3072
	global_load_dwordx4 v[124:127], v23, s[12:13]
	global_load_dwordx4 v[128:131], v24, s[12:13]
	global_load_dwordx4 v[132:135], v25, s[12:13]
	global_load_dwordx4 v[136:139], v26, s[12:13]
	v_lshl_add_u64 v[98:99], s[4:5], 0, v[16:17]
	s_add_i32 s2, s2, s48
	s_add_u32 s4, s4, s6
	s_addc_u32 s5, s5, s7
	s_add_u32 s10, s10, s6
	s_addc_u32 s11, s11, s7
	v_lshl_add_u64 v[18:19], v[18:19], 0, s[0:1]
	v_lshl_add_u64 v[20:21], v[20:21], 0, s[8:9]
	s_waitcnt vmcnt(17)
	s_branch .Lp4_loop
.Lp4_final_a:
	s_waitcnt vmcnt(0)
	ds_bpermute_b32 v46, v199, v48
	s_waitcnt lgkmcnt(0)
	v_add_f32_e32 v27, v48, v46
	ds_bpermute_b32 v46, v200, v27
	s_waitcnt lgkmcnt(0)
	v_add_f32_e32 v27, v27, v46
	ds_bpermute_b32 v46, v201, v27
	s_waitcnt lgkmcnt(0)
	v_add_f32_e32 v27, v27, v46
	ds_bpermute_b32 v46, v202, v27
	s_waitcnt lgkmcnt(0)
	v_add_f32_e32 v27, v27, v46
	v_fmamk_f32 v27, v27, 0x3a800000, v22
	v_mul_f32_e32 v46, 0x4b800000, v27
	v_cmp_gt_f32_e32 vcc, s3, v27
	s_nop 1
	v_cndmask_b32_e32 v27, v27, v46, vcc
	v_rsq_f32_e32 v27, v27
	s_nop 0
	v_mul_f32_e32 v46, 0x45800000, v27
	v_cndmask_b32_e32 v46, v27, v46, vcc
	v_lshlrev_b32_e32 v44, 16, v52
	v_and_b32_e32 v45, 0xffff0000, v52
	v_lshlrev_b32_e32 v40, 16, v53
	v_and_b32_e32 v41, 0xffff0000, v53
	v_pk_mul_f32 v[40:41], v[46:47], v[40:41] op_sel_hi:[0,1]
	v_pk_mul_f32 v[44:45], v[46:47], v[44:45] op_sel_hi:[0,1]
	v_pk_mul_f32 v[44:45], v[0:1], v[44:45]
	v_pk_mul_f32 v[40:41], v[2:3], v[40:41]
	v_pk_fma_f32 v[60:61], v[76:77], v[44:45], v[60:61]
	v_pk_fma_f32 v[62:63], v[78:79], v[40:41], v[62:63]
	global_store_dwordx4 v[50:51], v[60:63], off
	v_lshlrev_b32_e32 v44, 16, v54
	v_and_b32_e32 v45, 0xffff0000, v54
	v_lshlrev_b32_e32 v40, 16, v55
	v_and_b32_e32 v41, 0xffff0000, v55
	v_pk_mul_f32 v[40:41], v[46:47], v[40:41] op_sel_hi:[0,1]
	v_pk_mul_f32 v[44:45], v[46:47], v[44:45] op_sel_hi:[0,1]
	v_pk_mul_f32 v[44:45], v[4:5], v[44:45]
	v_pk_mul_f32 v[40:41], v[6:7], v[40:41]
	v_pk_fma_f32 v[64:65], v[80:81], v[44:45], v[64:65]
	v_pk_fma_f32 v[66:67], v[82:83], v[40:41], v[66:67]
	global_store_dwordx4 v[50:51], v[64:67], off offset:1024
	v_lshlrev_b32_e32 v44, 16, v56
	v_and_b32_e32 v45, 0xffff0000, v56
	v_lshlrev_b32_e32 v40, 16, v57
	v_and_b32_e32 v41, 0xffff0000, v57
	v_pk_mul_f32 v[40:41], v[46:47], v[40:41] op_sel_hi:[0,1]
	v_pk_mul_f32 v[44:45], v[46:47], v[44:45] op_sel_hi:[0,1]
	v_pk_mul_f32 v[44:45], v[8:9], v[44:45]
	v_pk_mul_f32 v[40:41], v[10:11], v[40:41]
	v_pk_fma_f32 v[68:69], v[84:85], v[44:45], v[68:69]
	v_pk_fma_f32 v[70:71], v[86:87], v[40:41], v[70:71]
	global_store_dwordx4 v[50:51], v[68:71], off offset:2048
	v_lshlrev_b32_e32 v44, 16, v58
	v_and_b32_e32 v45, 0xffff0000, v58
	v_lshlrev_b32_e32 v40, 16, v59
	v_and_b32_e32 v41, 0xffff0000, v59
	v_pk_mul_f32 v[40:41], v[46:47], v[40:41] op_sel_hi:[0,1]
	v_pk_mul_f32 v[44:45], v[46:47], v[44:45] op_sel_hi:[0,1]
	v_pk_mul_f32 v[44:45], v[12:13], v[44:45]
	v_pk_mul_f32 v[40:41], v[14:15], v[40:41]
	v_pk_fma_f32 v[72:73], v[88:89], v[44:45], v[72:73]
	v_pk_fma_f32 v[74:75], v[90:91], v[40:41], v[74:75]
	global_store_dwordx4 v[50:51], v[72:75], off offset:3072
	s_endpgm
.Lp4_final_b:
	s_waitcnt vmcnt(0)
	ds_bpermute_b32 v46, v199, v96
	s_waitcnt lgkmcnt(0)
	v_add_f32_e32 v27, v96, v46
	ds_bpermute_b32 v46, v200, v27
	s_waitcnt lgkmcnt(0)
	v_add_f32_e32 v27, v27, v46
	ds_bpermute_b32 v46, v201, v27
	s_waitcnt lgkmcnt(0)
	v_add_f32_e32 v27, v27, v46
	ds_bpermute_b32 v46, v202, v27
	s_waitcnt lgkmcnt(0)
	v_add_f32_e32 v27, v27, v46
	v_fmamk_f32 v27, v27, 0x3a800000, v22
	v_mul_f32_e32 v46, 0x4b800000, v27
	v_cmp_gt_f32_e32 vcc, s3, v27
	s_nop 1
	v_cndmask_b32_e32 v27, v27, v46, vcc
	v_rsq_f32_e32 v27, v27
	s_nop 0
	v_mul_f32_e32 v46, 0x45800000, v27
	v_cndmask_b32_e32 v46, v27, v46, vcc
	v_lshlrev_b32_e32 v44, 16, v100
	v_and_b32_e32 v45, 0xffff0000, v100
	v_lshlrev_b32_e32 v40, 16, v101
	v_and_b32_e32 v41, 0xffff0000, v101
	v_pk_mul_f32 v[40:41], v[46:47], v[40:41] op_sel_hi:[0,1]
	v_pk_mul_f32 v[44:45], v[46:47], v[44:45] op_sel_hi:[0,1]
	v_pk_mul_f32 v[44:45], v[0:1], v[44:45]
	v_pk_mul_f32 v[40:41], v[2:3], v[40:41]
	v_pk_fma_f32 v[108:109], v[124:125], v[44:45], v[108:109]
	v_pk_fma_f32 v[110:111], v[126:127], v[40:41], v[110:111]
	global_store_dwordx4 v[98:99], v[108:111], off
	v_lshlrev_b32_e32 v44, 16, v102
	v_and_b32_e32 v45, 0xffff0000, v102
	v_lshlrev_b32_e32 v40, 16, v103
	v_and_b32_e32 v41, 0xffff0000, v103
	v_pk_mul_f32 v[40:41], v[46:47], v[40:41] op_sel_hi:[0,1]
	v_pk_mul_f32 v[44:45], v[46:47], v[44:45] op_sel_hi:[0,1]
	v_pk_mul_f32 v[44:45], v[4:5], v[44:45]
	v_pk_mul_f32 v[40:41], v[6:7], v[40:41]
	v_pk_fma_f32 v[112:113], v[128:129], v[44:45], v[112:113]
	v_pk_fma_f32 v[114:115], v[130:131], v[40:41], v[114:115]
	global_store_dwordx4 v[98:99], v[112:115], off offset:1024
	v_lshlrev_b32_e32 v44, 16, v104
	v_and_b32_e32 v45, 0xffff0000, v104
	v_lshlrev_b32_e32 v40, 16, v105
	v_and_b32_e32 v41, 0xffff0000, v105
	v_pk_mul_f32 v[40:41], v[46:47], v[40:41] op_sel_hi:[0,1]
	v_pk_mul_f32 v[44:45], v[46:47], v[44:45] op_sel_hi:[0,1]
	v_pk_mul_f32 v[44:45], v[8:9], v[44:45]
	v_pk_mul_f32 v[40:41], v[10:11], v[40:41]
	v_pk_fma_f32 v[116:117], v[132:133], v[44:45], v[116:117]
	v_pk_fma_f32 v[118:119], v[134:135], v[40:41], v[118:119]
	global_store_dwordx4 v[98:99], v[116:119], off offset:2048
	v_lshlrev_b32_e32 v44, 16, v106
	v_and_b32_e32 v45, 0xffff0000, v106
	v_lshlrev_b32_e32 v40, 16, v107
	v_and_b32_e32 v41, 0xffff0000, v107
	v_pk_mul_f32 v[40:41], v[46:47], v[40:41] op_sel_hi:[0,1]
	v_pk_mul_f32 v[44:45], v[46:47], v[44:45] op_sel_hi:[0,1]
	v_pk_mul_f32 v[44:45], v[12:13], v[44:45]
	v_pk_mul_f32 v[40:41], v[14:15], v[40:41]
	v_pk_fma_f32 v[120:121], v[136:137], v[44:45], v[120:121]
	v_pk_fma_f32 v[122:123], v[138:139], v[40:41], v[122:123]
	global_store_dwordx4 v[98:99], v[120:123], off offset:3072
	s_endpgm
